# GEMM K loops: LDS-DMA loads whose vector address fed one load only now use the SGPR-base + VGPR-offset form (no 64-bit VALU add by the loading wave half)
# speedup vs baseline: 1.0069x; 1.0014x over previous
; #define PG8_STAGE(bufoff, gbase, voff) do { _Pragma("unroll") for (int _i = 0; _i < 2; ++_i) \
;         __builtin_amdgcn_global_load_lds((const unsigned*)((const char*)(gbase) + (voff)[_i]), (PG8_LAS unsigned*)(lds + (bufoff) + ldsw + _i * 8192), 16, 0, 0); } while (0)
; #define PG8_LDA(dst, b, h) do { _Pragma("unroll") for (int m = 0; m < 4; ++m) _Pragma("unroll") for (int k = 0; k < 2; ++k) dst[m][k] = *(const PG8_LAS bf16x8*)(lds + PG8_SA(b, h) + aoff + m * 2048 + k * 1024); } while (0)
; #define PG8_LDB(dst, b, h) do { _Pragma("unroll") for (int n = 0; n < 2; ++n) _Pragma("unroll") for (int k = 0; k < 2; ++k) dst[n][k] = *(const PG8_LAS bf16x8*)(lds + PG8_SB(b, h) + boff + n * 2048 + k * 1024); } while (0)
; #define PG8_MMA(ai, bj, At, Bt) do { __builtin_amdgcn_s_setprio(1); _Pragma("unroll") for (int m = 0; m < 4; ++m) _Pragma("unroll") for (int n = 0; n < 2; ++n) _Pragma("unroll") for (int k = 0; k < 2; ++k) \
;         acc[ai][bj][m][n] = __builtin_amdgcn_mfma_f32_16x16x32_bf16(Bt[n][k], At[m][k], acc[ai][bj][m][n], 0, 0, 0); __builtin_amdgcn_s_setprio(0); } while (0)
; #define PG8_WAIT_V(n) asm volatile("s_waitcnt vmcnt(" #n ")" ::: "memory")
; #define PG8_WAIT_L(n) asm volatile("s_waitcnt lgkmcnt(" #n ")" ::: "memory")
; #define PG8_BAR __builtin_amdgcn_s_barrier()
; #define PG8_SCHED __builtin_amdgcn_sched_barrier(0)
; template <class Epi, class Sched, bool ALIGN_EPI = false, bool SP2 = false>
; __device__ __forceinline__ void gemm_phase(PG8_LAS unsigned char* lds, const Gemm g, const Sched& S, const Epi& E) {
;     ...
;             PG8_LDB(B0, 0, 0); PG8_LDB(B1, 0, 1); PG8_SCHED; PG8_LDA(At, 0, 0); PG8_STAGE(PG8_SA(1, 1), a1 + hstep, voffA);
;             PG8_WAIT_V(8); PG8_WAIT_L(0); PG8_BAR; PG8_MMA(0, 0, At, B0); PG8_MMA(0, 1, At, B1); PG8_BAR; PG8_SCHED;
;             PG8_LDA(At, 0, 1); PG8_STAGE(PG8_SB(0, 0), b2, voffB); PG8_STAGE(PG8_SB(0, 1), b2 + hstep, voffB); PG8_STAGE(PG8_SA(0, 0), a2, voffA);
.LBB0_38:
	s_add_u32 s10, vcc_lo, 0xfff80080
	s_addc_u32 s11, vcc_hi, -1
	s_add_i32 s84, 0, 0x10000
	s_cmp_eq_u32 s13, 28
	s_cselect_b32 s69, s27, s11
	s_cselect_b32 s68, s86, s10
	s_cselect_b32 s11, s17, s12
	s_cselect_b32 s10, s88, s21
	s_add_i32 s93, 0, 0x14000
	v_add_u32_e32 v138, s84, v194
	v_add_u32_e32 v164, s93, v194
	ds_read_b128 v[114:117], v138
	ds_read_b128 v[118:121], v138 offset:1024
	ds_read_b128 v[130:133], v138 offset:2048
	ds_read_b128 v[138:141], v138 offset:3072
	ds_read_b128 v[146:149], v164
	ds_read_b128 v[156:159], v164 offset:1024
	ds_read_b128 v[160:163], v164 offset:2048
	ds_read_b128 v[164:167], v164 offset:3072
	s_add_i32 m0, s2, 0xc000
	ds_read_b128 v[168:171], v199
	ds_read_b128 v[172:175], v199 offset:1024
	ds_read_b128 v[176:179], v199 offset:2048
	ds_read_b128 v[180:183], v199 offset:3072
	ds_read_b128 v[184:187], v199 offset:4096
	ds_read_b128 v[188:191], v199 offset:5120
	ds_read_b128 v[200:203], v199 offset:6144
	ds_read_b128 v[204:207], v199 offset:7168
	global_load_lds_dwordx4 v152, vcc
	s_add_i32 m0, s2, 0xe000
	s_nop 0
	global_load_lds_dwordx4 v154, vcc
	s_waitcnt vmcnt(8)
	s_waitcnt lgkmcnt(0)
	s_setprio 1
	s_barrier
	v_mfma_f32_16x16x32_bf16 v[142:145], v[114:117], v[168:171], v[142:145]
	v_mfma_f32_16x16x32_bf16 v[62:65], v[130:133], v[168:171], v[62:65]
	v_mfma_f32_16x16x32_bf16 v[122:125], v[114:117], v[176:179], v[122:125]
	v_mfma_f32_16x16x32_bf16 v[50:53], v[130:133], v[176:179], v[50:53]
	v_mfma_f32_16x16x32_bf16 v[106:109], v[114:117], v[184:187], v[106:109]
	v_mfma_f32_16x16x32_bf16 v[42:45], v[130:133], v[184:187], v[42:45]
	v_mfma_f32_16x16x32_bf16 v[98:101], v[114:117], v[200:203], v[98:101]
	v_mfma_f32_16x16x32_bf16 v[34:37], v[130:133], v[200:203], v[34:37]
	v_mfma_f32_16x16x32_bf16 v[142:145], v[118:121], v[172:175], v[142:145]
	v_mfma_f32_16x16x32_bf16 v[62:65], v[138:141], v[172:175], v[62:65]
	v_mfma_f32_16x16x32_bf16 v[122:125], v[118:121], v[180:183], v[122:125]
	v_mfma_f32_16x16x32_bf16 v[50:53], v[138:141], v[180:183], v[50:53]
	v_mfma_f32_16x16x32_bf16 v[106:109], v[118:121], v[188:191], v[106:109]
	v_mfma_f32_16x16x32_bf16 v[42:45], v[138:141], v[188:191], v[42:45]
	v_mfma_f32_16x16x32_bf16 v[98:101], v[118:121], v[204:207], v[98:101]
	v_mfma_f32_16x16x32_bf16 v[34:37], v[138:141], v[204:207], v[34:37]
	v_mfma_f32_16x16x32_bf16 v[134:137], v[146:149], v[168:171], v[134:137]
	v_mfma_f32_16x16x32_bf16 v[58:61], v[160:163], v[168:171], v[58:61]
	v_mfma_f32_16x16x32_bf16 v[126:129], v[146:149], v[176:179], v[126:129]
	v_mfma_f32_16x16x32_bf16 v[54:57], v[160:163], v[176:179], v[54:57]
	v_mfma_f32_16x16x32_bf16 v[110:113], v[146:149], v[184:187], v[110:113]
	v_mfma_f32_16x16x32_bf16 v[46:49], v[160:163], v[184:187], v[46:49]
	v_mfma_f32_16x16x32_bf16 v[102:105], v[146:149], v[200:203], v[102:105]
	v_mfma_f32_16x16x32_bf16 v[38:41], v[160:163], v[200:203], v[38:41]
	v_mfma_f32_16x16x32_bf16 v[134:137], v[156:159], v[172:175], v[134:137]
	v_mfma_f32_16x16x32_bf16 v[58:61], v[164:167], v[172:175], v[58:61]
	v_mfma_f32_16x16x32_bf16 v[126:129], v[156:159], v[180:183], v[126:129]
	v_mfma_f32_16x16x32_bf16 v[54:57], v[164:167], v[180:183], v[54:57]
	v_mfma_f32_16x16x32_bf16 v[110:113], v[156:159], v[188:191], v[110:113]
	v_mfma_f32_16x16x32_bf16 v[46:49], v[164:167], v[188:191], v[46:49]
	v_mfma_f32_16x16x32_bf16 v[102:105], v[156:159], v[204:207], v[102:105]
	v_mfma_f32_16x16x32_bf16 v[38:41], v[164:167], v[204:207], v[38:41]
	s_barrier
	s_setprio 0
	s_add_i32 s84, s84, s1
	v_lshl_add_u64 v[208:209], s[10:11], 0, v[0:1]
	s_mov_b32 m0, s84
	ds_read_b128 v[168:171], v199 offset:16384
	ds_read_b128 v[172:175], v199 offset:17408
	ds_read_b128 v[176:179], v199 offset:18432
	ds_read_b128 v[180:183], v199 offset:19456
	ds_read_b128 v[184:187], v199 offset:20480
	ds_read_b128 v[188:191], v199 offset:21504
	ds_read_b128 v[200:203], v199 offset:22528
	ds_read_b128 v[204:207], v199 offset:23552
	global_load_lds_dwordx4 v[208:209], off
	s_add_i32 m0, s84, 0x2000
	s_add_u32 s84, s10, 0x80000
	v_lshl_add_u64 v[210:211], s[10:11], 0, v[150:151]
	s_addc_u32 s85, s11, 0
	s_add_i32 s93, s93, s1
	global_load_lds_dwordx4 v[210:211], off
	s_mov_b32 m0, s93
	v_lshl_add_u64 v[214:215], s[68:69], 0, v[150:151]
	global_load_lds_dwordx4 v0, s[84:85]
	s_add_i32 m0, s93, 0x2000
	s_nop 0
	global_load_lds_dwordx4 v150, s[84:85]
	v_lshl_add_u64 v[212:213], s[68:69], 0, v[0:1]
	s_mov_b32 m0, s2
	s_nop 0
	global_load_lds_dwordx4 v[212:213], off
	s_mov_b32 m0, s4
	s_nop 0
	global_load_lds_dwordx4 v[214:215], off
	s_waitcnt vmcnt(8)
	s_waitcnt lgkmcnt(0)
	s_setprio 1
	s_barrier
; #define PG8_STAGE(bufoff, gbase, voff) do { _Pragma("unroll") for (int _i = 0; _i < 2; ++_i) \
;         __builtin_amdgcn_global_load_lds((const unsigned*)((const char*)(gbase) + (voff)[_i]), (PG8_LAS unsigned*)(lds + (bufoff) + ldsw + _i * 8192), 16, 0, 0); } while (0)
; #define PG8_LDA(dst, b, h) do { _Pragma("unroll") for (int m = 0; m < 4; ++m) _Pragma("unroll") for (int k = 0; k < 2; ++k) dst[m][k] = *(const PG8_LAS bf16x8*)(lds + PG8_SA(b, h) + aoff + m * 2048 + k * 1024); } while (0)
; #define PG8_LDB(dst, b, h) do { _Pragma("unroll") for (int n = 0; n < 2; ++n) _Pragma("unroll") for (int k = 0; k < 2; ++k) dst[n][k] = *(const PG8_LAS bf16x8*)(lds + PG8_SB(b, h) + boff + n * 2048 + k * 1024); } while (0)
; #define PG8_MMA(ai, bj, At, Bt) do { __builtin_amdgcn_s_setprio(1); _Pragma("unroll") for (int m = 0; m < 4; ++m) _Pragma("unroll") for (int n = 0; n < 2; ++n) _Pragma("unroll") for (int k = 0; k < 2; ++k) \
;         acc[ai][bj][m][n] = __builtin_amdgcn_mfma_f32_16x16x32_bf16(Bt[n][k], At[m][k], acc[ai][bj][m][n], 0, 0, 0); __builtin_amdgcn_s_setprio(0); } while (0)
; #define PG8_WAIT_V(n) asm volatile("s_waitcnt vmcnt(" #n ")" ::: "memory")
; #define PG8_WAIT_L(n) asm volatile("s_waitcnt lgkmcnt(" #n ")" ::: "memory")
; #define PG8_BAR __builtin_amdgcn_s_barrier()
; #define PG8_SCHED __builtin_amdgcn_sched_barrier(0)
; template <class Epi, class Sched, bool ALIGN_EPI = false, bool SP2 = false>
; __device__ __forceinline__ void gemm_phase(PG8_LAS unsigned char* lds, const Gemm g, const Sched& S, const Epi& E) {
;     ...
;             PG8_WAIT_V(8); PG8_WAIT_L(0); PG8_BAR; PG8_MMA(1, 0, At, B0); PG8_MMA(1, 1, At, B1); PG8_BAR; PG8_SCHED;
;             PG8_LDB(B0, 1, 0); PG8_LDB(B1, 1, 1); PG8_SCHED; PG8_LDA(At, 1, 0); PG8_STAGE(PG8_SA(0, 1), a2 + hstep, voffA);
;             PG8_WAIT_V(8); PG8_WAIT_L(0); PG8_BAR; PG8_MMA(0, 0, At, B0); PG8_MMA(0, 1, At, B1); PG8_BAR; PG8_SCHED;
	v_mfma_f32_16x16x32_bf16 v[94:97], v[114:117], v[168:171], v[94:97]
	v_mfma_f32_16x16x32_bf16 v[30:33], v[130:133], v[168:171], v[30:33]
	v_mfma_f32_16x16x32_bf16 v[82:85], v[114:117], v[176:179], v[82:85]
	v_mfma_f32_16x16x32_bf16 v[18:21], v[130:133], v[176:179], v[18:21]
	v_mfma_f32_16x16x32_bf16 v[74:77], v[114:117], v[184:187], v[74:77]
	v_mfma_f32_16x16x32_bf16 v[10:13], v[130:133], v[184:187], v[10:13]
	v_mfma_f32_16x16x32_bf16 v[66:69], v[114:117], v[200:203], v[66:69]
	v_mfma_f32_16x16x32_bf16 v[2:5], v[130:133], v[200:203], v[2:5]
	v_mfma_f32_16x16x32_bf16 v[94:97], v[118:121], v[172:175], v[94:97]
	v_mfma_f32_16x16x32_bf16 v[30:33], v[138:141], v[172:175], v[30:33]
	v_mfma_f32_16x16x32_bf16 v[82:85], v[118:121], v[180:183], v[82:85]
	v_mfma_f32_16x16x32_bf16 v[18:21], v[138:141], v[180:183], v[18:21]
	v_mfma_f32_16x16x32_bf16 v[74:77], v[118:121], v[188:191], v[74:77]
	v_mfma_f32_16x16x32_bf16 v[10:13], v[138:141], v[188:191], v[10:13]
	v_mfma_f32_16x16x32_bf16 v[66:69], v[118:121], v[204:207], v[66:69]
	v_mfma_f32_16x16x32_bf16 v[2:5], v[138:141], v[204:207], v[2:5]
	v_mfma_f32_16x16x32_bf16 v[90:93], v[146:149], v[168:171], v[90:93]
	v_mfma_f32_16x16x32_bf16 v[26:29], v[160:163], v[168:171], v[26:29]
	v_mfma_f32_16x16x32_bf16 v[86:89], v[146:149], v[176:179], v[86:89]
	v_mfma_f32_16x16x32_bf16 v[22:25], v[160:163], v[176:179], v[22:25]
	v_mfma_f32_16x16x32_bf16 v[78:81], v[146:149], v[184:187], v[78:81]
	v_mfma_f32_16x16x32_bf16 v[14:17], v[160:163], v[184:187], v[14:17]
	v_mfma_f32_16x16x32_bf16 v[70:73], v[146:149], v[200:203], v[70:73]
	v_mfma_f32_16x16x32_bf16 v[6:9], v[160:163], v[200:203], v[6:9]
	v_mfma_f32_16x16x32_bf16 v[90:93], v[156:159], v[172:175], v[90:93]
	v_mfma_f32_16x16x32_bf16 v[26:29], v[164:167], v[172:175], v[26:29]
	v_mfma_f32_16x16x32_bf16 v[86:89], v[156:159], v[180:183], v[86:89]
	v_mfma_f32_16x16x32_bf16 v[22:25], v[164:167], v[180:183], v[22:25]
	v_mfma_f32_16x16x32_bf16 v[78:81], v[156:159], v[188:191], v[78:81]
	v_mfma_f32_16x16x32_bf16 v[14:17], v[164:167], v[188:191], v[14:17]
	v_mfma_f32_16x16x32_bf16 v[70:73], v[156:159], v[204:207], v[70:73]
	v_mfma_f32_16x16x32_bf16 v[6:9], v[164:167], v[204:207], v[6:9]
	s_barrier
	s_setprio 0
	s_add_i32 s84, 0, 0x18000
	s_add_i32 s85, 0, 0x1c000
	v_add_u32_e32 v138, s84, v194
	v_add_u32_e32 v164, s85, v194
	ds_read_b128 v[114:117], v138
	ds_read_b128 v[118:121], v138 offset:1024
	ds_read_b128 v[130:133], v138 offset:2048
	ds_read_b128 v[138:141], v138 offset:3072
	ds_read_b128 v[146:149], v164
	ds_read_b128 v[156:159], v164 offset:1024
	ds_read_b128 v[160:163], v164 offset:2048
	ds_read_b128 v[164:167], v164 offset:3072
	s_add_u32 s68, s68, 0x80000
	s_addc_u32 s69, s69, 0
	s_mov_b32 m0, s5
	ds_read_b128 v[168:171], v199 offset:32768
	ds_read_b128 v[172:175], v199 offset:33792
	ds_read_b128 v[176:179], v199 offset:34816
	ds_read_b128 v[180:183], v199 offset:35840
	ds_read_b128 v[184:187], v199 offset:36864
	ds_read_b128 v[188:191], v199 offset:37888
	ds_read_b128 v[200:203], v199 offset:38912
	ds_read_b128 v[204:207], v199 offset:39936
	global_load_lds_dwordx4 v0, s[68:69]
	s_mov_b32 m0, s6
	s_nop 0
	global_load_lds_dwordx4 v150, s[68:69]
	s_waitcnt vmcnt(8)
	s_waitcnt lgkmcnt(0)
	s_setprio 1
	s_barrier
	v_mfma_f32_16x16x32_bf16 v[142:145], v[114:117], v[168:171], v[142:145]
	v_mfma_f32_16x16x32_bf16 v[62:65], v[130:133], v[168:171], v[62:65]
	v_mfma_f32_16x16x32_bf16 v[122:125], v[114:117], v[176:179], v[122:125]
	v_mfma_f32_16x16x32_bf16 v[50:53], v[130:133], v[176:179], v[50:53]
	v_mfma_f32_16x16x32_bf16 v[106:109], v[114:117], v[184:187], v[106:109]
	v_mfma_f32_16x16x32_bf16 v[42:45], v[130:133], v[184:187], v[42:45]
	v_mfma_f32_16x16x32_bf16 v[98:101], v[114:117], v[200:203], v[98:101]
	v_mfma_f32_16x16x32_bf16 v[34:37], v[130:133], v[200:203], v[34:37]
	v_mfma_f32_16x16x32_bf16 v[142:145], v[118:121], v[172:175], v[142:145]
	v_mfma_f32_16x16x32_bf16 v[62:65], v[138:141], v[172:175], v[62:65]
	v_mfma_f32_16x16x32_bf16 v[122:125], v[118:121], v[180:183], v[122:125]
	v_mfma_f32_16x16x32_bf16 v[50:53], v[138:141], v[180:183], v[50:53]
	v_mfma_f32_16x16x32_bf16 v[106:109], v[118:121], v[188:191], v[106:109]
	v_mfma_f32_16x16x32_bf16 v[42:45], v[138:141], v[188:191], v[42:45]
	v_mfma_f32_16x16x32_bf16 v[98:101], v[118:121], v[204:207], v[98:101]
	v_mfma_f32_16x16x32_bf16 v[34:37], v[138:141], v[204:207], v[34:37]
	v_mfma_f32_16x16x32_bf16 v[134:137], v[146:149], v[168:171], v[134:137]
	v_mfma_f32_16x16x32_bf16 v[58:61], v[160:163], v[168:171], v[58:61]
	v_mfma_f32_16x16x32_bf16 v[126:129], v[146:149], v[176:179], v[126:129]
	v_mfma_f32_16x16x32_bf16 v[54:57], v[160:163], v[176:179], v[54:57]
	v_mfma_f32_16x16x32_bf16 v[110:113], v[146:149], v[184:187], v[110:113]
	v_mfma_f32_16x16x32_bf16 v[46:49], v[160:163], v[184:187], v[46:49]
	v_mfma_f32_16x16x32_bf16 v[102:105], v[146:149], v[200:203], v[102:105]
	v_mfma_f32_16x16x32_bf16 v[38:41], v[160:163], v[200:203], v[38:41]
	v_mfma_f32_16x16x32_bf16 v[134:137], v[156:159], v[172:175], v[134:137]
	v_mfma_f32_16x16x32_bf16 v[58:61], v[164:167], v[172:175], v[58:61]
	v_mfma_f32_16x16x32_bf16 v[126:129], v[156:159], v[180:183], v[126:129]
	v_mfma_f32_16x16x32_bf16 v[54:57], v[164:167], v[180:183], v[54:57]
	v_mfma_f32_16x16x32_bf16 v[110:113], v[156:159], v[188:191], v[110:113]
	v_mfma_f32_16x16x32_bf16 v[46:49], v[164:167], v[188:191], v[46:49]
	v_mfma_f32_16x16x32_bf16 v[102:105], v[156:159], v[204:207], v[102:105]
	v_mfma_f32_16x16x32_bf16 v[38:41], v[164:167], v[204:207], v[38:41]
	s_barrier
; #define PG8_STAGE(bufoff, gbase, voff) do { _Pragma("unroll") for (int _i = 0; _i < 2; ++_i) \
;         __builtin_amdgcn_global_load_lds((const unsigned*)((const char*)(gbase) + (voff)[_i]), (PG8_LAS unsigned*)(lds + (bufoff) + ldsw + _i * 8192), 16, 0, 0); } while (0)
; #define PG8_LDA(dst, b, h) do { _Pragma("unroll") for (int m = 0; m < 4; ++m) _Pragma("unroll") for (int k = 0; k < 2; ++k) dst[m][k] = *(const PG8_LAS bf16x8*)(lds + PG8_SA(b, h) + aoff + m * 2048 + k * 1024); } while (0)
; #define PG8_MMA(ai, bj, At, Bt) do { __builtin_amdgcn_s_setprio(1); _Pragma("unroll") for (int m = 0; m < 4; ++m) _Pragma("unroll") for (int n = 0; n < 2; ++n) _Pragma("unroll") for (int k = 0; k < 2; ++k) \
;         acc[ai][bj][m][n] = __builtin_amdgcn_mfma_f32_16x16x32_bf16(Bt[n][k], At[m][k], acc[ai][bj][m][n], 0, 0, 0); __builtin_amdgcn_s_setprio(0); } while (0)
; #define PG8_WAIT_V(n) asm volatile("s_waitcnt vmcnt(" #n ")" ::: "memory")
; #define PG8_WAIT_L(n) asm volatile("s_waitcnt lgkmcnt(" #n ")" ::: "memory")
; #define PG8_BAR __builtin_amdgcn_s_barrier()
; #define PG8_SCHED __builtin_amdgcn_sched_barrier(0)
; template <class Epi, class Sched, bool ALIGN_EPI = false, bool SP2 = false>
; __device__ __forceinline__ void gemm_phase(PG8_LAS unsigned char* lds, const Gemm g, const Sched& S, const Epi& E) {
;     ...
;             PG8_LDA(At, 1, 1); PG8_STAGE(PG8_SB(1, 0), b3, voffB); PG8_STAGE(PG8_SB(1, 1), b3 + hstep, voffB); PG8_STAGE(PG8_SA(1, 0), a3, voffA);
;             PG8_WAIT_V(8); PG8_WAIT_L(0); PG8_BAR; PG8_MMA(1, 0, At, B0); PG8_MMA(1, 1, At, B1); PG8_BAR; PG8_SCHED;
	s_setprio 0
	s_add_i32 s68, s84, s1
	v_lshl_add_u64 v[208:209], v[208:209], 0, s[34:35]
	s_mov_b32 m0, s68
	ds_read_b128 v[168:171], v199 offset:49152
	ds_read_b128 v[172:175], v199 offset:50176
	ds_read_b128 v[176:179], v199 offset:51200
	ds_read_b128 v[180:183], v199 offset:52224
	ds_read_b128 v[184:187], v199 offset:53248
	ds_read_b128 v[188:191], v199 offset:54272
	ds_read_b128 v[200:203], v199 offset:55296
	ds_read_b128 v[204:207], v199 offset:56320
	global_load_lds_dwordx4 v[208:209], off
	s_add_i32 m0, s68, 0x2000
	s_add_u32 s10, s10, 0x80080
	v_lshl_add_u64 v[208:209], v[210:211], 0, s[34:35]
	s_addc_u32 s11, s11, 0
	s_add_i32 s68, s85, s1
	global_load_lds_dwordx4 v[208:209], off
	s_mov_b32 m0, s68
	s_nop 0
	global_load_lds_dwordx4 v0, s[10:11]
	s_add_i32 m0, s68, 0x2000
	s_nop 0
	global_load_lds_dwordx4 v150, s[10:11]
	v_lshl_add_u64 v[208:209], v[212:213], 0, s[34:35]
	s_mov_b32 m0, s7
	s_nop 0
	global_load_lds_dwordx4 v[208:209], off
	v_lshl_add_u64 v[208:209], v[214:215], 0, s[34:35]
	s_mov_b32 m0, s30
	s_nop 0
	global_load_lds_dwordx4 v[208:209], off
	s_waitcnt vmcnt(8)
	s_waitcnt lgkmcnt(0)
	s_setprio 1
	s_barrier
	v_mfma_f32_16x16x32_bf16 v[94:97], v[114:117], v[168:171], v[94:97]
	v_mfma_f32_16x16x32_bf16 v[30:33], v[130:133], v[168:171], v[30:33]
	v_mfma_f32_16x16x32_bf16 v[82:85], v[114:117], v[176:179], v[82:85]
	v_mfma_f32_16x16x32_bf16 v[18:21], v[130:133], v[176:179], v[18:21]
	v_mfma_f32_16x16x32_bf16 v[74:77], v[114:117], v[184:187], v[74:77]
	v_mfma_f32_16x16x32_bf16 v[10:13], v[130:133], v[184:187], v[10:13]
	v_mfma_f32_16x16x32_bf16 v[66:69], v[114:117], v[200:203], v[66:69]
	v_mfma_f32_16x16x32_bf16 v[2:5], v[130:133], v[200:203], v[2:5]
	v_mfma_f32_16x16x32_bf16 v[94:97], v[118:121], v[172:175], v[94:97]
	v_mfma_f32_16x16x32_bf16 v[30:33], v[138:141], v[172:175], v[30:33]
	v_mfma_f32_16x16x32_bf16 v[82:85], v[118:121], v[180:183], v[82:85]
	v_mfma_f32_16x16x32_bf16 v[18:21], v[138:141], v[180:183], v[18:21]
	v_mfma_f32_16x16x32_bf16 v[74:77], v[118:121], v[188:191], v[74:77]
	v_mfma_f32_16x16x32_bf16 v[10:13], v[138:141], v[188:191], v[10:13]
	v_mfma_f32_16x16x32_bf16 v[66:69], v[118:121], v[204:207], v[66:69]
	v_mfma_f32_16x16x32_bf16 v[2:5], v[138:141], v[204:207], v[2:5]
	v_mfma_f32_16x16x32_bf16 v[90:93], v[146:149], v[168:171], v[90:93]
	v_mfma_f32_16x16x32_bf16 v[26:29], v[160:163], v[168:171], v[26:29]
	v_mfma_f32_16x16x32_bf16 v[86:89], v[146:149], v[176:179], v[86:89]
	v_mfma_f32_16x16x32_bf16 v[22:25], v[160:163], v[176:179], v[22:25]
	v_mfma_f32_16x16x32_bf16 v[78:81], v[146:149], v[184:187], v[78:81]
	v_mfma_f32_16x16x32_bf16 v[14:17], v[160:163], v[184:187], v[14:17]
	v_mfma_f32_16x16x32_bf16 v[70:73], v[146:149], v[200:203], v[70:73]
	v_mfma_f32_16x16x32_bf16 v[6:9], v[160:163], v[200:203], v[6:9]
	v_mfma_f32_16x16x32_bf16 v[90:93], v[156:159], v[172:175], v[90:93]
	v_mfma_f32_16x16x32_bf16 v[26:29], v[164:167], v[172:175], v[26:29]
	v_mfma_f32_16x16x32_bf16 v[86:89], v[156:159], v[180:183], v[86:89]
	v_mfma_f32_16x16x32_bf16 v[22:25], v[164:167], v[180:183], v[22:25]
	v_mfma_f32_16x16x32_bf16 v[78:81], v[156:159], v[188:191], v[78:81]
	v_mfma_f32_16x16x32_bf16 v[14:17], v[164:167], v[188:191], v[14:17]
	v_mfma_f32_16x16x32_bf16 v[70:73], v[156:159], v[204:207], v[70:73]
	v_mfma_f32_16x16x32_bf16 v[6:9], v[164:167], v[204:207], v[6:9]
	s_barrier
	s_setprio 0
	s_add_i32 s13, s13, 2
	s_add_u32 vcc_lo, vcc_lo, 0x100
	s_addc_u32 vcc_hi, vcc_hi, 0
	s_add_u32 s21, s21, 0x100
	s_addc_u32 s12, s12, 0
	s_cmp_gt_u32 s13, 29
	s_cbranch_scc0 .LBB0_38
	s_and_b64 vcc, exec, s[58:59]
	s_cbranch_vccz .LBB0_41
	s_barrier

; #define PG8_STAGE(bufoff, gbase, voff) do { _Pragma("unroll") for (int _i = 0; _i < 2; ++_i) \
;         __builtin_amdgcn_global_load_lds((const unsigned*)((const char*)(gbase) + (voff)[_i]), (PG8_LAS unsigned*)(lds + (bufoff) + ldsw + _i * 8192), 16, 0, 0); } while (0)
; #define PG8_LDA(dst, b, h) do { _Pragma("unroll") for (int m = 0; m < 4; ++m) _Pragma("unroll") for (int k = 0; k < 2; ++k) dst[m][k] = *(const PG8_LAS bf16x8*)(lds + PG8_SA(b, h) + aoff + m * 2048 + k * 1024); } while (0)
; #define PG8_LDB(dst, b, h) do { _Pragma("unroll") for (int n = 0; n < 2; ++n) _Pragma("unroll") for (int k = 0; k < 2; ++k) dst[n][k] = *(const PG8_LAS bf16x8*)(lds + PG8_SB(b, h) + boff + n * 2048 + k * 1024); } while (0)
; #define PG8_MMA(ai, bj, At, Bt) do { __builtin_amdgcn_s_setprio(1); _Pragma("unroll") for (int m = 0; m < 4; ++m) _Pragma("unroll") for (int n = 0; n < 2; ++n) _Pragma("unroll") for (int k = 0; k < 2; ++k) \
;         acc[ai][bj][m][n] = __builtin_amdgcn_mfma_f32_16x16x32_bf16(Bt[n][k], At[m][k], acc[ai][bj][m][n], 0, 0, 0); __builtin_amdgcn_s_setprio(0); } while (0)
; #define PG8_WAIT_V(n) asm volatile("s_waitcnt vmcnt(" #n ")" ::: "memory")
; #define PG8_WAIT_L(n) asm volatile("s_waitcnt lgkmcnt(" #n ")" ::: "memory")
; #define PG8_BAR __builtin_amdgcn_s_barrier()
; #define PG8_SCHED __builtin_amdgcn_sched_barrier(0)
; template <class Epi, class Sched, bool ALIGN_EPI = false, bool SP2 = false>
; __device__ __forceinline__ void gemm_phase(PG8_LAS unsigned char* lds, const Gemm g, const Sched& S, const Epi& E) {
;     ...
;             PG8_LDB(B0, 0, 0); PG8_LDB(B1, 0, 1); PG8_SCHED; PG8_LDA(At, 0, 0); PG8_STAGE(PG8_SA(1, 1), a1 + hstep, voffA);
;             PG8_WAIT_V(8); PG8_WAIT_L(0); PG8_BAR; PG8_MMA(0, 0, At, B0); PG8_MMA(0, 1, At, B1); PG8_BAR; PG8_SCHED;
;             PG8_LDA(At, 0, 1); PG8_STAGE(PG8_SB(0, 0), b2, voffB); PG8_STAGE(PG8_SB(0, 1), b2 + hstep, voffB); PG8_STAGE(PG8_SA(0, 0), a2, voffA);
.LBB0_169:
	s_add_u32 s10, s16, 0xfff80080
	s_addc_u32 s11, s17, -1
	s_add_i32 s21, 0, 0x10000
	s_cmp_eq_u32 s13, 28
	s_cselect_b32 s57, s43, s11
	s_cselect_b32 s56, s47, s10
	v_add_u32_e32 v148, s21, v151
	s_cselect_b32 s11, s45, s12
	s_cselect_b32 s10, s60, s61
	s_add_i32 s64, 0, 0x14000
	ds_read_b128 v[140:143], v148
	ds_read_b128 v[144:147], v148 offset:1024
	ds_read_b128 v[154:157], v148 offset:2048
	ds_read_b128 v[158:161], v148 offset:3072
	v_add_u32_e32 v148, s64, v151
	ds_read_b128 v[162:165], v148
	ds_read_b128 v[166:169], v148 offset:1024
	ds_read_b128 v[170:173], v148 offset:2048
	ds_read_b128 v[174:177], v148 offset:3072
	s_add_i32 m0, s2, 0xc000
	ds_read_b128 v[178:181], v153
	ds_read_b128 v[182:185], v153 offset:1024
	ds_read_b128 v[186:189], v153 offset:2048
	ds_read_b128 v[190:193], v153 offset:3072
	ds_read_b128 v[194:197], v153 offset:4096
	ds_read_b128 v[198:201], v153 offset:5120
	ds_read_b128 v[202:205], v153 offset:6144
	ds_read_b128 v[206:209], v153 offset:7168
	global_load_lds_dwordx4 v136, s[16:17]
	s_add_i32 m0, s2, 0xe000
	s_nop 0
	global_load_lds_dwordx4 v138, s[16:17]
	s_waitcnt vmcnt(8)
	s_waitcnt lgkmcnt(0)
	s_setprio 1
	s_barrier
	v_mfma_f32_16x16x32_bf16 v[126:129], v[140:143], v[178:181], v[126:129]
	v_mfma_f32_16x16x32_bf16 v[122:125], v[154:157], v[178:181], v[122:125]
	v_mfma_f32_16x16x32_bf16 v[110:113], v[140:143], v[186:189], v[110:113]
	v_mfma_f32_16x16x32_bf16 v[106:109], v[154:157], v[186:189], v[106:109]
	v_mfma_f32_16x16x32_bf16 v[94:97], v[140:143], v[194:197], v[94:97]
	v_mfma_f32_16x16x32_bf16 v[90:93], v[154:157], v[194:197], v[90:93]
	v_mfma_f32_16x16x32_bf16 v[78:81], v[140:143], v[202:205], v[78:81]
	v_mfma_f32_16x16x32_bf16 v[74:77], v[154:157], v[202:205], v[74:77]
	v_mfma_f32_16x16x32_bf16 v[126:129], v[144:147], v[182:185], v[126:129]
	v_mfma_f32_16x16x32_bf16 v[122:125], v[158:161], v[182:185], v[122:125]
	v_mfma_f32_16x16x32_bf16 v[110:113], v[144:147], v[190:193], v[110:113]
	v_mfma_f32_16x16x32_bf16 v[106:109], v[158:161], v[190:193], v[106:109]
	v_mfma_f32_16x16x32_bf16 v[94:97], v[144:147], v[198:201], v[94:97]
	v_mfma_f32_16x16x32_bf16 v[90:93], v[158:161], v[198:201], v[90:93]
	v_mfma_f32_16x16x32_bf16 v[78:81], v[144:147], v[206:209], v[78:81]
	v_mfma_f32_16x16x32_bf16 v[74:77], v[158:161], v[206:209], v[74:77]
	v_mfma_f32_16x16x32_bf16 v[118:121], v[162:165], v[178:181], v[118:121]
	v_mfma_f32_16x16x32_bf16 v[114:117], v[170:173], v[178:181], v[114:117]
	v_mfma_f32_16x16x32_bf16 v[102:105], v[162:165], v[186:189], v[102:105]
	v_mfma_f32_16x16x32_bf16 v[98:101], v[170:173], v[186:189], v[98:101]
	v_mfma_f32_16x16x32_bf16 v[86:89], v[162:165], v[194:197], v[86:89]
	v_mfma_f32_16x16x32_bf16 v[82:85], v[170:173], v[194:197], v[82:85]
	v_mfma_f32_16x16x32_bf16 v[70:73], v[162:165], v[202:205], v[70:73]
	v_mfma_f32_16x16x32_bf16 v[66:69], v[170:173], v[202:205], v[66:69]
	v_mfma_f32_16x16x32_bf16 v[118:121], v[166:169], v[182:185], v[118:121]
	v_mfma_f32_16x16x32_bf16 v[114:117], v[174:177], v[182:185], v[114:117]
	v_mfma_f32_16x16x32_bf16 v[102:105], v[166:169], v[190:193], v[102:105]
	v_mfma_f32_16x16x32_bf16 v[98:101], v[174:177], v[190:193], v[98:101]
	v_mfma_f32_16x16x32_bf16 v[86:89], v[166:169], v[198:201], v[86:89]
	v_mfma_f32_16x16x32_bf16 v[82:85], v[174:177], v[198:201], v[82:85]
	v_mfma_f32_16x16x32_bf16 v[70:73], v[166:169], v[206:209], v[70:73]
	v_mfma_f32_16x16x32_bf16 v[66:69], v[174:177], v[206:209], v[66:69]
	s_barrier
	s_setprio 0
	s_add_i32 s21, s21, s1
	v_lshl_add_u64 v[210:211], s[10:11], 0, v[0:1]
	s_mov_b32 m0, s21
	ds_read_b128 v[178:181], v153 offset:16384
	ds_read_b128 v[182:185], v153 offset:17408
	ds_read_b128 v[186:189], v153 offset:18432
	ds_read_b128 v[190:193], v153 offset:19456
	ds_read_b128 v[194:197], v153 offset:20480
	ds_read_b128 v[198:201], v153 offset:21504
	ds_read_b128 v[202:205], v153 offset:22528
	ds_read_b128 v[206:209], v153 offset:23552
	global_load_lds_dwordx4 v[210:211], off
	s_add_i32 m0, s21, 0x2000
	s_add_u32 s62, s10, 0x80000
	v_lshl_add_u64 v[212:213], s[10:11], 0, v[134:135]
	s_addc_u32 s63, s11, 0
	s_add_i32 s21, s64, s1
	global_load_lds_dwordx4 v[212:213], off
	s_mov_b32 m0, s21
	v_lshl_add_u64 v[216:217], s[56:57], 0, v[132:133]
	global_load_lds_dwordx4 v0, s[62:63]
	s_add_i32 m0, s21, 0x2000
	s_nop 0
	global_load_lds_dwordx4 v134, s[62:63]
	v_lshl_add_u64 v[214:215], s[56:57], 0, v[130:131]
	s_mov_b32 m0, s2
	s_nop 0
	global_load_lds_dwordx4 v[214:215], off
	s_mov_b32 m0, s4
	s_nop 0
	global_load_lds_dwordx4 v[216:217], off
	s_waitcnt vmcnt(8)
	s_waitcnt lgkmcnt(0)
	s_setprio 1
	s_barrier
; #define PG8_STAGE(bufoff, gbase, voff) do { _Pragma("unroll") for (int _i = 0; _i < 2; ++_i) \
;         __builtin_amdgcn_global_load_lds((const unsigned*)((const char*)(gbase) + (voff)[_i]), (PG8_LAS unsigned*)(lds + (bufoff) + ldsw + _i * 8192), 16, 0, 0); } while (0)
; #define PG8_LDA(dst, b, h) do { _Pragma("unroll") for (int m = 0; m < 4; ++m) _Pragma("unroll") for (int k = 0; k < 2; ++k) dst[m][k] = *(const PG8_LAS bf16x8*)(lds + PG8_SA(b, h) + aoff + m * 2048 + k * 1024); } while (0)
; #define PG8_LDB(dst, b, h) do { _Pragma("unroll") for (int n = 0; n < 2; ++n) _Pragma("unroll") for (int k = 0; k < 2; ++k) dst[n][k] = *(const PG8_LAS bf16x8*)(lds + PG8_SB(b, h) + boff + n * 2048 + k * 1024); } while (0)
; #define PG8_MMA(ai, bj, At, Bt) do { __builtin_amdgcn_s_setprio(1); _Pragma("unroll") for (int m = 0; m < 4; ++m) _Pragma("unroll") for (int n = 0; n < 2; ++n) _Pragma("unroll") for (int k = 0; k < 2; ++k) \
;         acc[ai][bj][m][n] = __builtin_amdgcn_mfma_f32_16x16x32_bf16(Bt[n][k], At[m][k], acc[ai][bj][m][n], 0, 0, 0); __builtin_amdgcn_s_setprio(0); } while (0)
; #define PG8_WAIT_V(n) asm volatile("s_waitcnt vmcnt(" #n ")" ::: "memory")
; #define PG8_WAIT_L(n) asm volatile("s_waitcnt lgkmcnt(" #n ")" ::: "memory")
; #define PG8_BAR __builtin_amdgcn_s_barrier()
; #define PG8_SCHED __builtin_amdgcn_sched_barrier(0)
; template <class Epi, class Sched, bool ALIGN_EPI = false, bool SP2 = false>
; __device__ __forceinline__ void gemm_phase(PG8_LAS unsigned char* lds, const Gemm g, const Sched& S, const Epi& E) {
;     ...
;             PG8_WAIT_V(8); PG8_WAIT_L(0); PG8_BAR; PG8_MMA(1, 0, At, B0); PG8_MMA(1, 1, At, B1); PG8_BAR; PG8_SCHED;
;             PG8_LDB(B0, 1, 0); PG8_LDB(B1, 1, 1); PG8_SCHED; PG8_LDA(At, 1, 0); PG8_STAGE(PG8_SA(0, 1), a2 + hstep, voffA);
;             PG8_WAIT_V(8); PG8_WAIT_L(0); PG8_BAR; PG8_MMA(0, 0, At, B0); PG8_MMA(0, 1, At, B1); PG8_BAR; PG8_SCHED;
	v_mfma_f32_16x16x32_bf16 v[62:65], v[140:143], v[178:181], v[62:65]
	v_mfma_f32_16x16x32_bf16 v[58:61], v[154:157], v[178:181], v[58:61]
	v_mfma_f32_16x16x32_bf16 v[46:49], v[140:143], v[186:189], v[46:49]
	v_mfma_f32_16x16x32_bf16 v[42:45], v[154:157], v[186:189], v[42:45]
	v_mfma_f32_16x16x32_bf16 v[30:33], v[140:143], v[194:197], v[30:33]
	v_mfma_f32_16x16x32_bf16 v[26:29], v[154:157], v[194:197], v[26:29]
	v_mfma_f32_16x16x32_bf16 v[14:17], v[140:143], v[202:205], v[14:17]
	v_mfma_f32_16x16x32_bf16 v[10:13], v[154:157], v[202:205], v[10:13]
	v_mfma_f32_16x16x32_bf16 v[62:65], v[144:147], v[182:185], v[62:65]
	v_mfma_f32_16x16x32_bf16 v[58:61], v[158:161], v[182:185], v[58:61]
	v_mfma_f32_16x16x32_bf16 v[46:49], v[144:147], v[190:193], v[46:49]
	v_mfma_f32_16x16x32_bf16 v[42:45], v[158:161], v[190:193], v[42:45]
	v_mfma_f32_16x16x32_bf16 v[30:33], v[144:147], v[198:201], v[30:33]
	v_mfma_f32_16x16x32_bf16 v[26:29], v[158:161], v[198:201], v[26:29]
	v_mfma_f32_16x16x32_bf16 v[14:17], v[144:147], v[206:209], v[14:17]
	v_mfma_f32_16x16x32_bf16 v[10:13], v[158:161], v[206:209], v[10:13]
	v_mfma_f32_16x16x32_bf16 v[54:57], v[162:165], v[178:181], v[54:57]
	v_mfma_f32_16x16x32_bf16 v[50:53], v[170:173], v[178:181], v[50:53]
	v_mfma_f32_16x16x32_bf16 v[38:41], v[162:165], v[186:189], v[38:41]
	v_mfma_f32_16x16x32_bf16 v[34:37], v[170:173], v[186:189], v[34:37]
	v_mfma_f32_16x16x32_bf16 v[22:25], v[162:165], v[194:197], v[22:25]
	v_mfma_f32_16x16x32_bf16 v[18:21], v[170:173], v[194:197], v[18:21]
	v_mfma_f32_16x16x32_bf16 v[6:9], v[162:165], v[202:205], v[6:9]
	v_mfma_f32_16x16x32_bf16 v[2:5], v[170:173], v[202:205], v[2:5]
	v_mfma_f32_16x16x32_bf16 v[54:57], v[166:169], v[182:185], v[54:57]
	v_mfma_f32_16x16x32_bf16 v[50:53], v[174:177], v[182:185], v[50:53]
	v_mfma_f32_16x16x32_bf16 v[38:41], v[166:169], v[190:193], v[38:41]
	v_mfma_f32_16x16x32_bf16 v[34:37], v[174:177], v[190:193], v[34:37]
	v_mfma_f32_16x16x32_bf16 v[22:25], v[166:169], v[198:201], v[22:25]
	v_mfma_f32_16x16x32_bf16 v[18:21], v[174:177], v[198:201], v[18:21]
	v_mfma_f32_16x16x32_bf16 v[6:9], v[166:169], v[206:209], v[6:9]
	v_mfma_f32_16x16x32_bf16 v[2:5], v[174:177], v[206:209], v[2:5]
	s_barrier
	s_setprio 0
	s_add_i32 s21, 0, 0x18000
	v_add_u32_e32 v148, s21, v151
	s_add_i32 s62, 0, 0x1c000
	ds_read_b128 v[140:143], v148
	ds_read_b128 v[144:147], v148 offset:1024
	ds_read_b128 v[154:157], v148 offset:2048
	ds_read_b128 v[158:161], v148 offset:3072
	v_add_u32_e32 v148, s62, v151
	ds_read_b128 v[162:165], v148
	ds_read_b128 v[166:169], v148 offset:1024
	ds_read_b128 v[170:173], v148 offset:2048
	ds_read_b128 v[174:177], v148 offset:3072
	s_add_u32 s56, s56, 0x80000
	s_addc_u32 s57, s57, 0
	s_mov_b32 m0, s5
	ds_read_b128 v[178:181], v153 offset:32768
	ds_read_b128 v[182:185], v153 offset:33792
	ds_read_b128 v[186:189], v153 offset:34816
	ds_read_b128 v[190:193], v153 offset:35840
	ds_read_b128 v[194:197], v153 offset:36864
	ds_read_b128 v[198:201], v153 offset:37888
	ds_read_b128 v[202:205], v153 offset:38912
	ds_read_b128 v[206:209], v153 offset:39936
	global_load_lds_dwordx4 v130, s[56:57]
	s_mov_b32 m0, s6
	s_nop 0
	global_load_lds_dwordx4 v132, s[56:57]
	s_waitcnt vmcnt(8)
	s_waitcnt lgkmcnt(0)
	s_setprio 1
	s_barrier
	v_mfma_f32_16x16x32_bf16 v[126:129], v[140:143], v[178:181], v[126:129]
	v_mfma_f32_16x16x32_bf16 v[122:125], v[154:157], v[178:181], v[122:125]
	v_mfma_f32_16x16x32_bf16 v[110:113], v[140:143], v[186:189], v[110:113]
	v_mfma_f32_16x16x32_bf16 v[106:109], v[154:157], v[186:189], v[106:109]
	v_mfma_f32_16x16x32_bf16 v[94:97], v[140:143], v[194:197], v[94:97]
	v_mfma_f32_16x16x32_bf16 v[90:93], v[154:157], v[194:197], v[90:93]
	v_mfma_f32_16x16x32_bf16 v[78:81], v[140:143], v[202:205], v[78:81]
	v_mfma_f32_16x16x32_bf16 v[74:77], v[154:157], v[202:205], v[74:77]
	v_mfma_f32_16x16x32_bf16 v[126:129], v[144:147], v[182:185], v[126:129]
	v_mfma_f32_16x16x32_bf16 v[122:125], v[158:161], v[182:185], v[122:125]
	v_mfma_f32_16x16x32_bf16 v[110:113], v[144:147], v[190:193], v[110:113]
	v_mfma_f32_16x16x32_bf16 v[106:109], v[158:161], v[190:193], v[106:109]
	v_mfma_f32_16x16x32_bf16 v[94:97], v[144:147], v[198:201], v[94:97]
	v_mfma_f32_16x16x32_bf16 v[90:93], v[158:161], v[198:201], v[90:93]
	v_mfma_f32_16x16x32_bf16 v[78:81], v[144:147], v[206:209], v[78:81]
	v_mfma_f32_16x16x32_bf16 v[74:77], v[158:161], v[206:209], v[74:77]
	v_mfma_f32_16x16x32_bf16 v[118:121], v[162:165], v[178:181], v[118:121]
	v_mfma_f32_16x16x32_bf16 v[114:117], v[170:173], v[178:181], v[114:117]
	v_mfma_f32_16x16x32_bf16 v[102:105], v[162:165], v[186:189], v[102:105]
	v_mfma_f32_16x16x32_bf16 v[98:101], v[170:173], v[186:189], v[98:101]
	v_mfma_f32_16x16x32_bf16 v[86:89], v[162:165], v[194:197], v[86:89]
	v_mfma_f32_16x16x32_bf16 v[82:85], v[170:173], v[194:197], v[82:85]
	v_mfma_f32_16x16x32_bf16 v[70:73], v[162:165], v[202:205], v[70:73]
	v_mfma_f32_16x16x32_bf16 v[66:69], v[170:173], v[202:205], v[66:69]
	v_mfma_f32_16x16x32_bf16 v[118:121], v[166:169], v[182:185], v[118:121]
	v_mfma_f32_16x16x32_bf16 v[114:117], v[174:177], v[182:185], v[114:117]
	v_mfma_f32_16x16x32_bf16 v[102:105], v[166:169], v[190:193], v[102:105]
	v_mfma_f32_16x16x32_bf16 v[98:101], v[174:177], v[190:193], v[98:101]
	v_mfma_f32_16x16x32_bf16 v[86:89], v[166:169], v[198:201], v[86:89]
	v_mfma_f32_16x16x32_bf16 v[82:85], v[174:177], v[198:201], v[82:85]
	v_mfma_f32_16x16x32_bf16 v[70:73], v[166:169], v[206:209], v[70:73]
	v_mfma_f32_16x16x32_bf16 v[66:69], v[174:177], v[206:209], v[66:69]
	s_barrier
; #define PG8_STAGE(bufoff, gbase, voff) do { _Pragma("unroll") for (int _i = 0; _i < 2; ++_i) \
;         __builtin_amdgcn_global_load_lds((const unsigned*)((const char*)(gbase) + (voff)[_i]), (PG8_LAS unsigned*)(lds + (bufoff) + ldsw + _i * 8192), 16, 0, 0); } while (0)
; #define PG8_LDA(dst, b, h) do { _Pragma("unroll") for (int m = 0; m < 4; ++m) _Pragma("unroll") for (int k = 0; k < 2; ++k) dst[m][k] = *(const PG8_LAS bf16x8*)(lds + PG8_SA(b, h) + aoff + m * 2048 + k * 1024); } while (0)
; #define PG8_MMA(ai, bj, At, Bt) do { __builtin_amdgcn_s_setprio(1); _Pragma("unroll") for (int m = 0; m < 4; ++m) _Pragma("unroll") for (int n = 0; n < 2; ++n) _Pragma("unroll") for (int k = 0; k < 2; ++k) \
;         acc[ai][bj][m][n] = __builtin_amdgcn_mfma_f32_16x16x32_bf16(Bt[n][k], At[m][k], acc[ai][bj][m][n], 0, 0, 0); __builtin_amdgcn_s_setprio(0); } while (0)
; #define PG8_WAIT_V(n) asm volatile("s_waitcnt vmcnt(" #n ")" ::: "memory")
; #define PG8_WAIT_L(n) asm volatile("s_waitcnt lgkmcnt(" #n ")" ::: "memory")
; #define PG8_BAR __builtin_amdgcn_s_barrier()
; #define PG8_SCHED __builtin_amdgcn_sched_barrier(0)
; template <class Epi, class Sched, bool ALIGN_EPI = false, bool SP2 = false>
; __device__ __forceinline__ void gemm_phase(PG8_LAS unsigned char* lds, const Gemm g, const Sched& S, const Epi& E) {
;     ...
;             PG8_WAIT_V(8); PG8_WAIT_L(0); PG8_BAR; PG8_MMA(0, 0, At, B0); PG8_MMA(0, 1, At, B1); PG8_BAR; PG8_SCHED;
;             PG8_LDA(At, 1, 1); PG8_STAGE(PG8_SB(1, 0), b3, voffB); PG8_STAGE(PG8_SB(1, 1), b3 + hstep, voffB); PG8_STAGE(PG8_SA(1, 0), a3, voffA);
;             PG8_WAIT_V(8); PG8_WAIT_L(0); PG8_BAR; PG8_MMA(1, 0, At, B0); PG8_MMA(1, 1, At, B1); PG8_BAR; PG8_SCHED;
	s_setprio 0
	s_add_i32 s21, s21, s1
	v_lshl_add_u64 v[210:211], v[210:211], 0, s[34:35]
	s_mov_b32 m0, s21
	ds_read_b128 v[178:181], v153 offset:49152
	ds_read_b128 v[182:185], v153 offset:50176
	ds_read_b128 v[186:189], v153 offset:51200
	ds_read_b128 v[190:193], v153 offset:52224
	ds_read_b128 v[194:197], v153 offset:53248
	ds_read_b128 v[198:201], v153 offset:54272
	ds_read_b128 v[202:205], v153 offset:55296
	ds_read_b128 v[206:209], v153 offset:56320
	global_load_lds_dwordx4 v[210:211], off
	s_add_i32 m0, s21, 0x2000
	s_add_u32 s10, s10, 0x80080
	v_lshl_add_u64 v[210:211], v[212:213], 0, s[34:35]
	s_addc_u32 s11, s11, 0
	s_add_i32 s21, s62, s1
	global_load_lds_dwordx4 v[210:211], off
	s_mov_b32 m0, s21
	s_nop 0
	global_load_lds_dwordx4 v0, s[10:11]
	s_add_i32 m0, s21, 0x2000
	s_nop 0
	global_load_lds_dwordx4 v134, s[10:11]
	v_lshl_add_u64 v[210:211], v[214:215], 0, s[34:35]
	s_mov_b32 m0, s7
	s_nop 0
	global_load_lds_dwordx4 v[210:211], off
	v_lshl_add_u64 v[210:211], v[216:217], 0, s[34:35]
	s_mov_b32 m0, s30
	s_nop 0
	global_load_lds_dwordx4 v[210:211], off
	s_waitcnt vmcnt(8)
	s_waitcnt lgkmcnt(0)
	s_setprio 1
	s_barrier
	v_mfma_f32_16x16x32_bf16 v[62:65], v[140:143], v[178:181], v[62:65]
	v_mfma_f32_16x16x32_bf16 v[58:61], v[154:157], v[178:181], v[58:61]
	v_mfma_f32_16x16x32_bf16 v[46:49], v[140:143], v[186:189], v[46:49]
	v_mfma_f32_16x16x32_bf16 v[42:45], v[154:157], v[186:189], v[42:45]
	v_mfma_f32_16x16x32_bf16 v[30:33], v[140:143], v[194:197], v[30:33]
	v_mfma_f32_16x16x32_bf16 v[26:29], v[154:157], v[194:197], v[26:29]
	v_mfma_f32_16x16x32_bf16 v[14:17], v[140:143], v[202:205], v[14:17]
	v_mfma_f32_16x16x32_bf16 v[10:13], v[154:157], v[202:205], v[10:13]
	v_mfma_f32_16x16x32_bf16 v[62:65], v[144:147], v[182:185], v[62:65]
	v_mfma_f32_16x16x32_bf16 v[58:61], v[158:161], v[182:185], v[58:61]
	v_mfma_f32_16x16x32_bf16 v[46:49], v[144:147], v[190:193], v[46:49]
	v_mfma_f32_16x16x32_bf16 v[42:45], v[158:161], v[190:193], v[42:45]
	v_mfma_f32_16x16x32_bf16 v[30:33], v[144:147], v[198:201], v[30:33]
	v_mfma_f32_16x16x32_bf16 v[26:29], v[158:161], v[198:201], v[26:29]
	v_mfma_f32_16x16x32_bf16 v[14:17], v[144:147], v[206:209], v[14:17]
	v_mfma_f32_16x16x32_bf16 v[10:13], v[158:161], v[206:209], v[10:13]
	v_mfma_f32_16x16x32_bf16 v[54:57], v[162:165], v[178:181], v[54:57]
	v_mfma_f32_16x16x32_bf16 v[50:53], v[170:173], v[178:181], v[50:53]
	v_mfma_f32_16x16x32_bf16 v[38:41], v[162:165], v[186:189], v[38:41]
	v_mfma_f32_16x16x32_bf16 v[34:37], v[170:173], v[186:189], v[34:37]
	v_mfma_f32_16x16x32_bf16 v[22:25], v[162:165], v[194:197], v[22:25]
	v_mfma_f32_16x16x32_bf16 v[18:21], v[170:173], v[194:197], v[18:21]
	v_mfma_f32_16x16x32_bf16 v[6:9], v[162:165], v[202:205], v[6:9]
	v_mfma_f32_16x16x32_bf16 v[2:5], v[170:173], v[202:205], v[2:5]
	v_mfma_f32_16x16x32_bf16 v[54:57], v[166:169], v[182:185], v[54:57]
	v_mfma_f32_16x16x32_bf16 v[50:53], v[174:177], v[182:185], v[50:53]
	v_mfma_f32_16x16x32_bf16 v[38:41], v[166:169], v[190:193], v[38:41]
	v_mfma_f32_16x16x32_bf16 v[34:37], v[174:177], v[190:193], v[34:37]
	v_mfma_f32_16x16x32_bf16 v[22:25], v[166:169], v[198:201], v[22:25]
	v_mfma_f32_16x16x32_bf16 v[18:21], v[174:177], v[198:201], v[18:21]
	v_mfma_f32_16x16x32_bf16 v[6:9], v[166:169], v[206:209], v[6:9]
	v_mfma_f32_16x16x32_bf16 v[2:5], v[174:177], v[206:209], v[2:5]
	s_barrier
	s_setprio 0
	s_add_i32 s13, s13, 2
	s_add_u32 s16, s16, 0x100
	s_addc_u32 s17, s17, 0
	s_add_u32 s61, s61, 0x100
	s_addc_u32 s12, s12, 0
	s_cmp_gt_u32 s13, 29
	s_cbranch_scc0 .LBB0_169
	s_and_b64 vcc, exec, s[22:23]
	s_cbranch_vccz .LBB0_172
	s_barrier

; #define PG8_STAGE(bufoff, gbase, voff) do { _Pragma("unroll") for (int _i = 0; _i < 2; ++_i) \
;         __builtin_amdgcn_global_load_lds((const unsigned*)((const char*)(gbase) + (voff)[_i]), (PG8_LAS unsigned*)(lds + (bufoff) + ldsw + _i * 8192), 16, 0, 0); } while (0)
; #define PG8_LDA(dst, b, h) do { _Pragma("unroll") for (int m = 0; m < 4; ++m) _Pragma("unroll") for (int k = 0; k < 2; ++k) dst[m][k] = *(const PG8_LAS bf16x8*)(lds + PG8_SA(b, h) + aoff + m * 2048 + k * 1024); } while (0)
; #define PG8_LDB(dst, b, h) do { _Pragma("unroll") for (int n = 0; n < 2; ++n) _Pragma("unroll") for (int k = 0; k < 2; ++k) dst[n][k] = *(const PG8_LAS bf16x8*)(lds + PG8_SB(b, h) + boff + n * 2048 + k * 1024); } while (0)
; #define PG8_MMA(ai, bj, At, Bt) do { __builtin_amdgcn_s_setprio(1); _Pragma("unroll") for (int m = 0; m < 4; ++m) _Pragma("unroll") for (int n = 0; n < 2; ++n) _Pragma("unroll") for (int k = 0; k < 2; ++k) \
;         acc[ai][bj][m][n] = __builtin_amdgcn_mfma_f32_16x16x32_bf16(Bt[n][k], At[m][k], acc[ai][bj][m][n], 0, 0, 0); __builtin_amdgcn_s_setprio(0); } while (0)
; #define PG8_WAIT_V(n) asm volatile("s_waitcnt vmcnt(" #n ")" ::: "memory")
; #define PG8_WAIT_L(n) asm volatile("s_waitcnt lgkmcnt(" #n ")" ::: "memory")
; #define PG8_BAR __builtin_amdgcn_s_barrier()
; #define PG8_SCHED __builtin_amdgcn_sched_barrier(0)
; template <class Epi, class Sched, bool ALIGN_EPI = false, bool SP2 = false>
; __device__ __forceinline__ void gemm_phase(PG8_LAS unsigned char* lds, const Gemm g, const Sched& S, const Epi& E) {
;     ...
;             PG8_LDB(B0, 0, 0); PG8_LDB(B1, 0, 1); PG8_SCHED; PG8_LDA(At, 0, 0); PG8_STAGE(PG8_SA(1, 1), a1 + hstep, voffA);
;             PG8_WAIT_V(8); PG8_WAIT_L(0); PG8_BAR; PG8_MMA(0, 0, At, B0); PG8_MMA(0, 1, At, B1); PG8_BAR; PG8_SCHED;
;             PG8_LDA(At, 0, 1); PG8_STAGE(PG8_SB(0, 0), b2, voffB); PG8_STAGE(PG8_SB(0, 1), b2 + hstep, voffB); PG8_STAGE(PG8_SA(0, 0), a2, voffA);
;             PG8_WAIT_V(8); PG8_WAIT_L(0); PG8_BAR; PG8_MMA(1, 0, At, B0); PG8_MMA(1, 1, At, B1); PG8_BAR; PG8_SCHED;
.LBB0_223:
	s_add_i32 s14, s10, 2
	s_add_u32 s15, s8, 0x80
	s_addc_u32 s11, s9, 0
	s_add_i32 s64, 0, 0x10000
	s_cmp_eq_u32 s57, s10
	s_cselect_b32 s11, s51, s11
	s_cselect_b32 s10, s50, s15
	s_cselect_b32 s45, s53, s13
	s_cselect_b32 s44, s52, s12
	s_add_i32 s15, 0, 0x14000
	v_add_u32_e32 v156, s64, v145
	v_add_u32_e32 v172, s15, v145
	ds_read_b128 v[140:143], v156
	ds_read_b128 v[148:151], v156 offset:1024
	ds_read_b128 v[152:155], v156 offset:2048
	ds_read_b128 v[156:159], v156 offset:3072
	ds_read_b128 v[160:163], v172
	ds_read_b128 v[164:167], v172 offset:1024
	ds_read_b128 v[168:171], v172 offset:2048
	ds_read_b128 v[172:175], v172 offset:3072
	s_add_i32 m0, s21, 0xc000
	ds_read_b128 v[176:179], v147
	ds_read_b128 v[180:183], v147 offset:1024
	ds_read_b128 v[184:187], v147 offset:2048
	ds_read_b128 v[188:191], v147 offset:3072
	ds_read_b128 v[192:195], v147 offset:4096
	ds_read_b128 v[196:199], v147 offset:5120
	ds_read_b128 v[200:203], v147 offset:6144
	ds_read_b128 v[204:207], v147 offset:7168
	global_load_lds_dwordx4 v136, s[8:9]
	s_add_i32 m0, s21, 0xe000
	s_nop 0
	global_load_lds_dwordx4 v138, s[8:9]
	s_waitcnt vmcnt(8)
	s_waitcnt lgkmcnt(0)
	s_setprio 1
	s_barrier
	v_mfma_f32_16x16x32_bf16 v[126:129], v[140:143], v[176:179], v[126:129]
	v_mfma_f32_16x16x32_bf16 v[122:125], v[152:155], v[176:179], v[122:125]
	v_mfma_f32_16x16x32_bf16 v[110:113], v[140:143], v[184:187], v[110:113]
	v_mfma_f32_16x16x32_bf16 v[106:109], v[152:155], v[184:187], v[106:109]
	v_mfma_f32_16x16x32_bf16 v[94:97], v[140:143], v[192:195], v[94:97]
	v_mfma_f32_16x16x32_bf16 v[90:93], v[152:155], v[192:195], v[90:93]
	v_mfma_f32_16x16x32_bf16 v[78:81], v[140:143], v[200:203], v[78:81]
	v_mfma_f32_16x16x32_bf16 v[74:77], v[152:155], v[200:203], v[74:77]
	v_mfma_f32_16x16x32_bf16 v[126:129], v[148:151], v[180:183], v[126:129]
	v_mfma_f32_16x16x32_bf16 v[122:125], v[156:159], v[180:183], v[122:125]
	v_mfma_f32_16x16x32_bf16 v[110:113], v[148:151], v[188:191], v[110:113]
	v_mfma_f32_16x16x32_bf16 v[106:109], v[156:159], v[188:191], v[106:109]
	v_mfma_f32_16x16x32_bf16 v[94:97], v[148:151], v[196:199], v[94:97]
	v_mfma_f32_16x16x32_bf16 v[90:93], v[156:159], v[196:199], v[90:93]
	v_mfma_f32_16x16x32_bf16 v[78:81], v[148:151], v[204:207], v[78:81]
	v_mfma_f32_16x16x32_bf16 v[74:77], v[156:159], v[204:207], v[74:77]
	v_mfma_f32_16x16x32_bf16 v[118:121], v[160:163], v[176:179], v[118:121]
	v_mfma_f32_16x16x32_bf16 v[114:117], v[168:171], v[176:179], v[114:117]
	v_mfma_f32_16x16x32_bf16 v[102:105], v[160:163], v[184:187], v[102:105]
	v_mfma_f32_16x16x32_bf16 v[98:101], v[168:171], v[184:187], v[98:101]
	v_mfma_f32_16x16x32_bf16 v[86:89], v[160:163], v[192:195], v[86:89]
	v_mfma_f32_16x16x32_bf16 v[82:85], v[168:171], v[192:195], v[82:85]
	v_mfma_f32_16x16x32_bf16 v[70:73], v[160:163], v[200:203], v[70:73]
	v_mfma_f32_16x16x32_bf16 v[66:69], v[168:171], v[200:203], v[66:69]
	v_mfma_f32_16x16x32_bf16 v[118:121], v[164:167], v[180:183], v[118:121]
	v_mfma_f32_16x16x32_bf16 v[114:117], v[172:175], v[180:183], v[114:117]
	v_mfma_f32_16x16x32_bf16 v[102:105], v[164:167], v[188:191], v[102:105]
	v_mfma_f32_16x16x32_bf16 v[98:101], v[172:175], v[188:191], v[98:101]
	v_mfma_f32_16x16x32_bf16 v[86:89], v[164:167], v[196:199], v[86:89]
	v_mfma_f32_16x16x32_bf16 v[82:85], v[172:175], v[196:199], v[82:85]
	v_mfma_f32_16x16x32_bf16 v[70:73], v[164:167], v[204:207], v[70:73]
	v_mfma_f32_16x16x32_bf16 v[66:69], v[172:175], v[204:207], v[66:69]
	s_barrier
	s_setprio 0
	s_add_i32 s64, s64, s7
	v_lshl_add_u64 v[208:209], s[44:45], 0, v[0:1]
	s_mov_b32 m0, s64
	ds_read_b128 v[176:179], v147 offset:16384
	ds_read_b128 v[180:183], v147 offset:17408
	ds_read_b128 v[184:187], v147 offset:18432
	ds_read_b128 v[188:191], v147 offset:19456
	ds_read_b128 v[192:195], v147 offset:20480
	ds_read_b128 v[196:199], v147 offset:21504
	ds_read_b128 v[200:203], v147 offset:22528
	ds_read_b128 v[204:207], v147 offset:23552
	global_load_lds_dwordx4 v[208:209], off
	s_add_i32 m0, s64, 0x2000
	v_lshl_add_u64 v[210:211], s[44:45], 0, v[134:135]
	s_add_u32 s44, s44, s30
	s_addc_u32 s45, s45, 0
	s_add_i32 s15, s15, s7
	global_load_lds_dwordx4 v[210:211], off
	v_lshl_add_u64 v[212:213], s[44:45], 0, v[0:1]
	s_mov_b32 m0, s15
	v_lshl_add_u64 v[214:215], s[44:45], 0, v[134:135]
	global_load_lds_dwordx4 v[212:213], off
	s_add_i32 m0, s15, 0x2000
	v_lshl_add_u64 v[216:217], s[10:11], 0, v[130:131]
	global_load_lds_dwordx4 v[214:215], off
	s_mov_b32 m0, s21
	v_lshl_add_u64 v[222:223], s[10:11], 0, v[132:133]
	global_load_lds_dwordx4 v[216:217], off
	s_mov_b32 m0, s26
	s_nop 0
	global_load_lds_dwordx4 v[222:223], off
	s_waitcnt vmcnt(8)
	s_waitcnt lgkmcnt(0)
	s_setprio 1
	s_barrier
; #define PG8_STAGE(bufoff, gbase, voff) do { _Pragma("unroll") for (int _i = 0; _i < 2; ++_i) \
;         __builtin_amdgcn_global_load_lds((const unsigned*)((const char*)(gbase) + (voff)[_i]), (PG8_LAS unsigned*)(lds + (bufoff) + ldsw + _i * 8192), 16, 0, 0); } while (0)
; #define PG8_LDA(dst, b, h) do { _Pragma("unroll") for (int m = 0; m < 4; ++m) _Pragma("unroll") for (int k = 0; k < 2; ++k) dst[m][k] = *(const PG8_LAS bf16x8*)(lds + PG8_SA(b, h) + aoff + m * 2048 + k * 1024); } while (0)
; #define PG8_LDB(dst, b, h) do { _Pragma("unroll") for (int n = 0; n < 2; ++n) _Pragma("unroll") for (int k = 0; k < 2; ++k) dst[n][k] = *(const PG8_LAS bf16x8*)(lds + PG8_SB(b, h) + boff + n * 2048 + k * 1024); } while (0)
; #define PG8_MMA(ai, bj, At, Bt) do { __builtin_amdgcn_s_setprio(1); _Pragma("unroll") for (int m = 0; m < 4; ++m) _Pragma("unroll") for (int n = 0; n < 2; ++n) _Pragma("unroll") for (int k = 0; k < 2; ++k) \
;         acc[ai][bj][m][n] = __builtin_amdgcn_mfma_f32_16x16x32_bf16(Bt[n][k], At[m][k], acc[ai][bj][m][n], 0, 0, 0); __builtin_amdgcn_s_setprio(0); } while (0)
; #define PG8_WAIT_V(n) asm volatile("s_waitcnt vmcnt(" #n ")" ::: "memory")
; #define PG8_WAIT_L(n) asm volatile("s_waitcnt lgkmcnt(" #n ")" ::: "memory")
; #define PG8_BAR __builtin_amdgcn_s_barrier()
; #define PG8_SCHED __builtin_amdgcn_sched_barrier(0)
; template <class Epi, class Sched, bool ALIGN_EPI = false, bool SP2 = false>
; __device__ __forceinline__ void gemm_phase(PG8_LAS unsigned char* lds, const Gemm g, const Sched& S, const Epi& E) {
;     ...
;             PG8_WAIT_V(8); PG8_WAIT_L(0); PG8_BAR; PG8_MMA(1, 0, At, B0); PG8_MMA(1, 1, At, B1); PG8_BAR; PG8_SCHED;
;             PG8_LDB(B0, 1, 0); PG8_LDB(B1, 1, 1); PG8_SCHED; PG8_LDA(At, 1, 0); PG8_STAGE(PG8_SA(0, 1), a2 + hstep, voffA);
;             PG8_WAIT_V(8); PG8_WAIT_L(0); PG8_BAR; PG8_MMA(0, 0, At, B0); PG8_MMA(0, 1, At, B1); PG8_BAR; PG8_SCHED;
	v_mfma_f32_16x16x32_bf16 v[62:65], v[140:143], v[176:179], v[62:65]
	v_mfma_f32_16x16x32_bf16 v[58:61], v[152:155], v[176:179], v[58:61]
	v_mfma_f32_16x16x32_bf16 v[46:49], v[140:143], v[184:187], v[46:49]
	v_mfma_f32_16x16x32_bf16 v[42:45], v[152:155], v[184:187], v[42:45]
	v_mfma_f32_16x16x32_bf16 v[30:33], v[140:143], v[192:195], v[30:33]
	v_mfma_f32_16x16x32_bf16 v[26:29], v[152:155], v[192:195], v[26:29]
	v_mfma_f32_16x16x32_bf16 v[14:17], v[140:143], v[200:203], v[14:17]
	v_mfma_f32_16x16x32_bf16 v[10:13], v[152:155], v[200:203], v[10:13]
	v_mfma_f32_16x16x32_bf16 v[62:65], v[148:151], v[180:183], v[62:65]
	v_mfma_f32_16x16x32_bf16 v[58:61], v[156:159], v[180:183], v[58:61]
	v_mfma_f32_16x16x32_bf16 v[46:49], v[148:151], v[188:191], v[46:49]
	v_mfma_f32_16x16x32_bf16 v[42:45], v[156:159], v[188:191], v[42:45]
	v_mfma_f32_16x16x32_bf16 v[30:33], v[148:151], v[196:199], v[30:33]
	v_mfma_f32_16x16x32_bf16 v[26:29], v[156:159], v[196:199], v[26:29]
	v_mfma_f32_16x16x32_bf16 v[14:17], v[148:151], v[204:207], v[14:17]
	v_mfma_f32_16x16x32_bf16 v[10:13], v[156:159], v[204:207], v[10:13]
	v_mfma_f32_16x16x32_bf16 v[54:57], v[160:163], v[176:179], v[54:57]
	v_mfma_f32_16x16x32_bf16 v[50:53], v[168:171], v[176:179], v[50:53]
	v_mfma_f32_16x16x32_bf16 v[38:41], v[160:163], v[184:187], v[38:41]
	v_mfma_f32_16x16x32_bf16 v[34:37], v[168:171], v[184:187], v[34:37]
	v_mfma_f32_16x16x32_bf16 v[22:25], v[160:163], v[192:195], v[22:25]
	v_mfma_f32_16x16x32_bf16 v[18:21], v[168:171], v[192:195], v[18:21]
	v_mfma_f32_16x16x32_bf16 v[6:9], v[160:163], v[200:203], v[6:9]
	v_mfma_f32_16x16x32_bf16 v[2:5], v[168:171], v[200:203], v[2:5]
	v_mfma_f32_16x16x32_bf16 v[54:57], v[164:167], v[180:183], v[54:57]
	v_mfma_f32_16x16x32_bf16 v[50:53], v[172:175], v[180:183], v[50:53]
	v_mfma_f32_16x16x32_bf16 v[38:41], v[164:167], v[188:191], v[38:41]
	v_mfma_f32_16x16x32_bf16 v[34:37], v[172:175], v[188:191], v[34:37]
	v_mfma_f32_16x16x32_bf16 v[22:25], v[164:167], v[196:199], v[22:25]
	v_mfma_f32_16x16x32_bf16 v[18:21], v[172:175], v[196:199], v[18:21]
	v_mfma_f32_16x16x32_bf16 v[6:9], v[164:167], v[204:207], v[6:9]
	v_mfma_f32_16x16x32_bf16 v[2:5], v[172:175], v[204:207], v[2:5]
	s_barrier
	s_setprio 0
	s_add_i32 s15, 0, 0x18000
	s_add_i32 s44, 0, 0x1c000
	v_add_u32_e32 v156, s15, v145
	v_add_u32_e32 v172, s44, v145
	ds_read_b128 v[140:143], v156
	ds_read_b128 v[148:151], v156 offset:1024
	ds_read_b128 v[152:155], v156 offset:2048
	ds_read_b128 v[156:159], v156 offset:3072
	ds_read_b128 v[160:163], v172
	ds_read_b128 v[164:167], v172 offset:1024
	ds_read_b128 v[168:171], v172 offset:2048
	ds_read_b128 v[172:175], v172 offset:3072
	s_add_u32 s10, s10, s30
	s_addc_u32 s11, s11, 0
	s_mov_b32 m0, s27
	ds_read_b128 v[176:179], v147 offset:32768
	ds_read_b128 v[180:183], v147 offset:33792
	ds_read_b128 v[184:187], v147 offset:34816
	ds_read_b128 v[188:191], v147 offset:35840
	ds_read_b128 v[192:195], v147 offset:36864
	ds_read_b128 v[196:199], v147 offset:37888
	ds_read_b128 v[200:203], v147 offset:38912
	ds_read_b128 v[204:207], v147 offset:39936
	global_load_lds_dwordx4 v130, s[10:11]
	s_mov_b32 m0, s54
	s_nop 0
	global_load_lds_dwordx4 v132, s[10:11]
	s_waitcnt vmcnt(8)
	s_waitcnt lgkmcnt(0)
	s_setprio 1
	s_barrier
	v_mfma_f32_16x16x32_bf16 v[126:129], v[140:143], v[176:179], v[126:129]
	v_mfma_f32_16x16x32_bf16 v[122:125], v[152:155], v[176:179], v[122:125]
	v_mfma_f32_16x16x32_bf16 v[110:113], v[140:143], v[184:187], v[110:113]
	v_mfma_f32_16x16x32_bf16 v[106:109], v[152:155], v[184:187], v[106:109]
	v_mfma_f32_16x16x32_bf16 v[94:97], v[140:143], v[192:195], v[94:97]
	v_mfma_f32_16x16x32_bf16 v[90:93], v[152:155], v[192:195], v[90:93]
	v_mfma_f32_16x16x32_bf16 v[78:81], v[140:143], v[200:203], v[78:81]
	v_mfma_f32_16x16x32_bf16 v[74:77], v[152:155], v[200:203], v[74:77]
	v_mfma_f32_16x16x32_bf16 v[126:129], v[148:151], v[180:183], v[126:129]
	v_mfma_f32_16x16x32_bf16 v[122:125], v[156:159], v[180:183], v[122:125]
	v_mfma_f32_16x16x32_bf16 v[110:113], v[148:151], v[188:191], v[110:113]
	v_mfma_f32_16x16x32_bf16 v[106:109], v[156:159], v[188:191], v[106:109]
	v_mfma_f32_16x16x32_bf16 v[94:97], v[148:151], v[196:199], v[94:97]
	v_mfma_f32_16x16x32_bf16 v[90:93], v[156:159], v[196:199], v[90:93]
	v_mfma_f32_16x16x32_bf16 v[78:81], v[148:151], v[204:207], v[78:81]
	v_mfma_f32_16x16x32_bf16 v[74:77], v[156:159], v[204:207], v[74:77]
	v_mfma_f32_16x16x32_bf16 v[118:121], v[160:163], v[176:179], v[118:121]
	v_mfma_f32_16x16x32_bf16 v[114:117], v[168:171], v[176:179], v[114:117]
	v_mfma_f32_16x16x32_bf16 v[102:105], v[160:163], v[184:187], v[102:105]
	v_mfma_f32_16x16x32_bf16 v[98:101], v[168:171], v[184:187], v[98:101]
	v_mfma_f32_16x16x32_bf16 v[86:89], v[160:163], v[192:195], v[86:89]
	v_mfma_f32_16x16x32_bf16 v[82:85], v[168:171], v[192:195], v[82:85]
	v_mfma_f32_16x16x32_bf16 v[70:73], v[160:163], v[200:203], v[70:73]
	v_mfma_f32_16x16x32_bf16 v[66:69], v[168:171], v[200:203], v[66:69]
	v_mfma_f32_16x16x32_bf16 v[118:121], v[164:167], v[180:183], v[118:121]
	v_mfma_f32_16x16x32_bf16 v[114:117], v[172:175], v[180:183], v[114:117]
	v_mfma_f32_16x16x32_bf16 v[102:105], v[164:167], v[188:191], v[102:105]
	v_mfma_f32_16x16x32_bf16 v[98:101], v[172:175], v[188:191], v[98:101]
	v_mfma_f32_16x16x32_bf16 v[86:89], v[164:167], v[196:199], v[86:89]
	v_mfma_f32_16x16x32_bf16 v[82:85], v[172:175], v[196:199], v[82:85]
	v_mfma_f32_16x16x32_bf16 v[70:73], v[164:167], v[204:207], v[70:73]
	v_mfma_f32_16x16x32_bf16 v[66:69], v[172:175], v[204:207], v[66:69]
	s_barrier
; #define PG8_STAGE(bufoff, gbase, voff) do { _Pragma("unroll") for (int _i = 0; _i < 2; ++_i) \
;         __builtin_amdgcn_global_load_lds((const unsigned*)((const char*)(gbase) + (voff)[_i]), (PG8_LAS unsigned*)(lds + (bufoff) + ldsw + _i * 8192), 16, 0, 0); } while (0)
; #define PG8_LDA(dst, b, h) do { _Pragma("unroll") for (int m = 0; m < 4; ++m) _Pragma("unroll") for (int k = 0; k < 2; ++k) dst[m][k] = *(const PG8_LAS bf16x8*)(lds + PG8_SA(b, h) + aoff + m * 2048 + k * 1024); } while (0)
; #define PG8_MMA(ai, bj, At, Bt) do { __builtin_amdgcn_s_setprio(1); _Pragma("unroll") for (int m = 0; m < 4; ++m) _Pragma("unroll") for (int n = 0; n < 2; ++n) _Pragma("unroll") for (int k = 0; k < 2; ++k) \
;         acc[ai][bj][m][n] = __builtin_amdgcn_mfma_f32_16x16x32_bf16(Bt[n][k], At[m][k], acc[ai][bj][m][n], 0, 0, 0); __builtin_amdgcn_s_setprio(0); } while (0)
; #define PG8_WAIT_V(n) asm volatile("s_waitcnt vmcnt(" #n ")" ::: "memory")
; #define PG8_WAIT_L(n) asm volatile("s_waitcnt lgkmcnt(" #n ")" ::: "memory")
; #define PG8_BAR __builtin_amdgcn_s_barrier()
; #define PG8_SCHED __builtin_amdgcn_sched_barrier(0)
; template <class Epi, class Sched, bool ALIGN_EPI = false, bool SP2 = false>
; __device__ __forceinline__ void gemm_phase(PG8_LAS unsigned char* lds, const Gemm g, const Sched& S, const Epi& E) {
;     ...
;             PG8_WAIT_V(8); PG8_WAIT_L(0); PG8_BAR; PG8_MMA(0, 0, At, B0); PG8_MMA(0, 1, At, B1); PG8_BAR; PG8_SCHED;
;             PG8_LDA(At, 1, 1); PG8_STAGE(PG8_SB(1, 0), b3, voffB); PG8_STAGE(PG8_SB(1, 1), b3 + hstep, voffB); PG8_STAGE(PG8_SA(1, 0), a3, voffA);
;             PG8_WAIT_V(8); PG8_WAIT_L(0); PG8_BAR; PG8_MMA(1, 0, At, B0); PG8_MMA(1, 1, At, B1); PG8_BAR; PG8_SCHED;
	s_setprio 0
	s_add_i32 s10, s15, s7
	v_lshl_add_u64 v[208:209], v[208:209], 0, s[34:35]
	s_mov_b32 m0, s10
	ds_read_b128 v[176:179], v147 offset:49152
	ds_read_b128 v[180:183], v147 offset:50176
	ds_read_b128 v[184:187], v147 offset:51200
	ds_read_b128 v[188:191], v147 offset:52224
	ds_read_b128 v[192:195], v147 offset:53248
	ds_read_b128 v[196:199], v147 offset:54272
	ds_read_b128 v[200:203], v147 offset:55296
	ds_read_b128 v[204:207], v147 offset:56320
	global_load_lds_dwordx4 v[208:209], off
	v_lshl_add_u64 v[208:209], v[210:211], 0, s[34:35]
	s_add_i32 m0, s10, 0x2000
	s_add_i32 s10, s44, s7
	global_load_lds_dwordx4 v[208:209], off
	v_lshl_add_u64 v[208:209], v[212:213], 0, s[34:35]
	s_mov_b32 m0, s10
	s_nop 0
	global_load_lds_dwordx4 v[208:209], off
	v_lshl_add_u64 v[208:209], v[214:215], 0, s[34:35]
	s_add_i32 m0, s10, 0x2000
	s_nop 0
	global_load_lds_dwordx4 v[208:209], off
	v_lshl_add_u64 v[208:209], v[216:217], 0, s[34:35]
	s_mov_b32 m0, s16
	s_nop 0
	global_load_lds_dwordx4 v[208:209], off
	v_lshl_add_u64 v[208:209], v[222:223], 0, s[34:35]
	s_mov_b32 m0, s17
	s_nop 0
	global_load_lds_dwordx4 v[208:209], off
	s_waitcnt vmcnt(8)
	s_waitcnt lgkmcnt(0)
	s_setprio 1
	s_barrier
	v_mfma_f32_16x16x32_bf16 v[62:65], v[140:143], v[176:179], v[62:65]
	v_mfma_f32_16x16x32_bf16 v[58:61], v[152:155], v[176:179], v[58:61]
	v_mfma_f32_16x16x32_bf16 v[46:49], v[140:143], v[184:187], v[46:49]
	v_mfma_f32_16x16x32_bf16 v[42:45], v[152:155], v[184:187], v[42:45]
	v_mfma_f32_16x16x32_bf16 v[30:33], v[140:143], v[192:195], v[30:33]
	v_mfma_f32_16x16x32_bf16 v[26:29], v[152:155], v[192:195], v[26:29]
	v_mfma_f32_16x16x32_bf16 v[14:17], v[140:143], v[200:203], v[14:17]
	v_mfma_f32_16x16x32_bf16 v[10:13], v[152:155], v[200:203], v[10:13]
	v_mfma_f32_16x16x32_bf16 v[62:65], v[148:151], v[180:183], v[62:65]
	v_mfma_f32_16x16x32_bf16 v[58:61], v[156:159], v[180:183], v[58:61]
	v_mfma_f32_16x16x32_bf16 v[46:49], v[148:151], v[188:191], v[46:49]
	v_mfma_f32_16x16x32_bf16 v[42:45], v[156:159], v[188:191], v[42:45]
	v_mfma_f32_16x16x32_bf16 v[30:33], v[148:151], v[196:199], v[30:33]
	v_mfma_f32_16x16x32_bf16 v[26:29], v[156:159], v[196:199], v[26:29]
	v_mfma_f32_16x16x32_bf16 v[14:17], v[148:151], v[204:207], v[14:17]
	v_mfma_f32_16x16x32_bf16 v[10:13], v[156:159], v[204:207], v[10:13]
	v_mfma_f32_16x16x32_bf16 v[54:57], v[160:163], v[176:179], v[54:57]
	v_mfma_f32_16x16x32_bf16 v[50:53], v[168:171], v[176:179], v[50:53]
	v_mfma_f32_16x16x32_bf16 v[38:41], v[160:163], v[184:187], v[38:41]
	v_mfma_f32_16x16x32_bf16 v[34:37], v[168:171], v[184:187], v[34:37]
	v_mfma_f32_16x16x32_bf16 v[22:25], v[160:163], v[192:195], v[22:25]
	v_mfma_f32_16x16x32_bf16 v[18:21], v[168:171], v[192:195], v[18:21]
	v_mfma_f32_16x16x32_bf16 v[6:9], v[160:163], v[200:203], v[6:9]
	v_mfma_f32_16x16x32_bf16 v[2:5], v[168:171], v[200:203], v[2:5]
	v_mfma_f32_16x16x32_bf16 v[54:57], v[164:167], v[180:183], v[54:57]
	v_mfma_f32_16x16x32_bf16 v[50:53], v[172:175], v[180:183], v[50:53]
	v_mfma_f32_16x16x32_bf16 v[38:41], v[164:167], v[188:191], v[38:41]
	v_mfma_f32_16x16x32_bf16 v[34:37], v[172:175], v[188:191], v[34:37]
	v_mfma_f32_16x16x32_bf16 v[22:25], v[164:167], v[196:199], v[22:25]
	v_mfma_f32_16x16x32_bf16 v[18:21], v[172:175], v[196:199], v[18:21]
	v_mfma_f32_16x16x32_bf16 v[6:9], v[164:167], v[204:207], v[6:9]
	v_mfma_f32_16x16x32_bf16 v[2:5], v[172:175], v[204:207], v[2:5]
	s_barrier
	s_setprio 0
	s_add_u32 s8, s8, 0x100
	s_addc_u32 s9, s9, 0
	s_add_u32 s12, s12, 0x100
	s_addc_u32 s13, s13, 0
	s_cmp_ge_u32 s14, s56
	s_mov_b32 s10, s14
	s_cbranch_scc0 .LBB0_223
	s_and_b64 vcc, exec, s[46:47]
	s_cbranch_vccz .LBB0_226
	s_barrier

; #define PG8_STAGE(bufoff, gbase, voff) do { _Pragma("unroll") for (int _i = 0; _i < 2; ++_i) \
;         __builtin_amdgcn_global_load_lds((const unsigned*)((const char*)(gbase) + (voff)[_i]), (PG8_LAS unsigned*)(lds + (bufoff) + ldsw + _i * 8192), 16, 0, 0); } while (0)
; #define PG8_LDA(dst, b, h) do { _Pragma("unroll") for (int m = 0; m < 4; ++m) _Pragma("unroll") for (int k = 0; k < 2; ++k) dst[m][k] = *(const PG8_LAS bf16x8*)(lds + PG8_SA(b, h) + aoff + m * 2048 + k * 1024); } while (0)
; #define PG8_LDB(dst, b, h) do { _Pragma("unroll") for (int n = 0; n < 2; ++n) _Pragma("unroll") for (int k = 0; k < 2; ++k) dst[n][k] = *(const PG8_LAS bf16x8*)(lds + PG8_SB(b, h) + boff + n * 2048 + k * 1024); } while (0)
; #define PG8_MMA(ai, bj, At, Bt) do { __builtin_amdgcn_s_setprio(1); _Pragma("unroll") for (int m = 0; m < 4; ++m) _Pragma("unroll") for (int n = 0; n < 2; ++n) _Pragma("unroll") for (int k = 0; k < 2; ++k) \
;         acc[ai][bj][m][n] = __builtin_amdgcn_mfma_f32_16x16x32_bf16(Bt[n][k], At[m][k], acc[ai][bj][m][n], 0, 0, 0); __builtin_amdgcn_s_setprio(0); } while (0)
; #define PG8_WAIT_V(n) asm volatile("s_waitcnt vmcnt(" #n ")" ::: "memory")
; #define PG8_WAIT_L(n) asm volatile("s_waitcnt lgkmcnt(" #n ")" ::: "memory")
; #define PG8_BAR __builtin_amdgcn_s_barrier()
; #define PG8_SCHED __builtin_amdgcn_sched_barrier(0)
; template <class Epi, class Sched, bool ALIGN_EPI = false, bool SP2 = false>
; __device__ __forceinline__ void gemm_phase(PG8_LAS unsigned char* lds, const Gemm g, const Sched& S, const Epi& E) {
;     ...
;             PG8_LDB(B0, 0, 0); PG8_LDB(B1, 0, 1); PG8_SCHED; PG8_LDA(At, 0, 0); PG8_STAGE(PG8_SA(1, 1), a1 + hstep, voffA);
;             PG8_WAIT_V(8); PG8_WAIT_L(0); PG8_BAR; PG8_MMA(0, 0, At, B0); PG8_MMA(0, 1, At, B1); PG8_BAR; PG8_SCHED;
;             PG8_LDA(At, 0, 1); PG8_STAGE(PG8_SB(0, 0), b2, voffB); PG8_STAGE(PG8_SB(0, 1), b2 + hstep, voffB); PG8_STAGE(PG8_SA(0, 0), a2, voffA);
;             PG8_WAIT_V(8); PG8_WAIT_L(0); PG8_BAR; PG8_MMA(1, 0, At, B0); PG8_MMA(1, 1, At, B1); PG8_BAR; PG8_SCHED;
.LBB0_559:
	s_add_u32 s10, s50, 0xfff80080
	s_addc_u32 s11, s51, -1
	s_add_i32 s60, 0, 0x10000
	s_cmp_eq_u32 s59, 28
	s_cselect_b32 s53, s37, s11
	s_cselect_b32 s52, s43, s10
	v_add_u32_e32 v144, s60, v149
	s_cselect_b32 s11, s23, s58
	s_cselect_b32 s10, s56, s57
	s_add_i32 s62, 0, 0x14000
	ds_read_b128 v[140:143], v144
	ds_read_b128 v[152:155], v144 offset:1024
	ds_read_b128 v[156:159], v144 offset:2048
	ds_read_b128 v[160:163], v144 offset:3072
	v_add_u32_e32 v144, s62, v149
	ds_read_b128 v[164:167], v144
	ds_read_b128 v[168:171], v144 offset:1024
	ds_read_b128 v[172:175], v144 offset:2048
	ds_read_b128 v[176:179], v144 offset:3072
	s_add_i32 m0, s5, 0xc000
	ds_read_b128 v[180:183], v151
	ds_read_b128 v[184:187], v151 offset:1024
	ds_read_b128 v[188:191], v151 offset:2048
	ds_read_b128 v[192:195], v151 offset:3072
	ds_read_b128 v[196:199], v151 offset:4096
	ds_read_b128 v[200:203], v151 offset:5120
	ds_read_b128 v[204:207], v151 offset:6144
	ds_read_b128 v[208:211], v151 offset:7168
	global_load_lds_dwordx4 v136, s[50:51]
	s_add_i32 m0, s5, 0xe000
	s_nop 0
	global_load_lds_dwordx4 v138, s[50:51]
	s_waitcnt vmcnt(8)
	s_waitcnt lgkmcnt(0)
	s_setprio 1
	s_barrier
	v_mfma_f32_16x16x32_bf16 v[126:129], v[140:143], v[180:183], v[126:129]
	v_mfma_f32_16x16x32_bf16 v[122:125], v[156:159], v[180:183], v[122:125]
	v_mfma_f32_16x16x32_bf16 v[110:113], v[140:143], v[188:191], v[110:113]
	v_mfma_f32_16x16x32_bf16 v[106:109], v[156:159], v[188:191], v[106:109]
	v_mfma_f32_16x16x32_bf16 v[94:97], v[140:143], v[196:199], v[94:97]
	v_mfma_f32_16x16x32_bf16 v[90:93], v[156:159], v[196:199], v[90:93]
	v_mfma_f32_16x16x32_bf16 v[78:81], v[140:143], v[204:207], v[78:81]
	v_mfma_f32_16x16x32_bf16 v[74:77], v[156:159], v[204:207], v[74:77]
	v_mfma_f32_16x16x32_bf16 v[126:129], v[152:155], v[184:187], v[126:129]
	v_mfma_f32_16x16x32_bf16 v[122:125], v[160:163], v[184:187], v[122:125]
	v_mfma_f32_16x16x32_bf16 v[110:113], v[152:155], v[192:195], v[110:113]
	v_mfma_f32_16x16x32_bf16 v[106:109], v[160:163], v[192:195], v[106:109]
	v_mfma_f32_16x16x32_bf16 v[94:97], v[152:155], v[200:203], v[94:97]
	v_mfma_f32_16x16x32_bf16 v[90:93], v[160:163], v[200:203], v[90:93]
	v_mfma_f32_16x16x32_bf16 v[78:81], v[152:155], v[208:211], v[78:81]
	v_mfma_f32_16x16x32_bf16 v[74:77], v[160:163], v[208:211], v[74:77]
	v_mfma_f32_16x16x32_bf16 v[118:121], v[164:167], v[180:183], v[118:121]
	v_mfma_f32_16x16x32_bf16 v[114:117], v[172:175], v[180:183], v[114:117]
	v_mfma_f32_16x16x32_bf16 v[102:105], v[164:167], v[188:191], v[102:105]
	v_mfma_f32_16x16x32_bf16 v[98:101], v[172:175], v[188:191], v[98:101]
	v_mfma_f32_16x16x32_bf16 v[86:89], v[164:167], v[196:199], v[86:89]
	v_mfma_f32_16x16x32_bf16 v[82:85], v[172:175], v[196:199], v[82:85]
	v_mfma_f32_16x16x32_bf16 v[70:73], v[164:167], v[204:207], v[70:73]
	v_mfma_f32_16x16x32_bf16 v[66:69], v[172:175], v[204:207], v[66:69]
	v_mfma_f32_16x16x32_bf16 v[118:121], v[168:171], v[184:187], v[118:121]
	v_mfma_f32_16x16x32_bf16 v[114:117], v[176:179], v[184:187], v[114:117]
	v_mfma_f32_16x16x32_bf16 v[102:105], v[168:171], v[192:195], v[102:105]
	v_mfma_f32_16x16x32_bf16 v[98:101], v[176:179], v[192:195], v[98:101]
	v_mfma_f32_16x16x32_bf16 v[86:89], v[168:171], v[200:203], v[86:89]
	v_mfma_f32_16x16x32_bf16 v[82:85], v[176:179], v[200:203], v[82:85]
	v_mfma_f32_16x16x32_bf16 v[70:73], v[168:171], v[208:211], v[70:73]
	v_mfma_f32_16x16x32_bf16 v[66:69], v[176:179], v[208:211], v[66:69]
	s_barrier
	s_setprio 0
	s_add_i32 s60, s60, s4
	v_lshl_add_u64 v[144:145], s[10:11], 0, v[0:1]
	s_mov_b32 m0, s60
	ds_read_b128 v[180:183], v151 offset:16384
	ds_read_b128 v[184:187], v151 offset:17408
	ds_read_b128 v[188:191], v151 offset:18432
	ds_read_b128 v[192:195], v151 offset:19456
	ds_read_b128 v[196:199], v151 offset:20480
	ds_read_b128 v[200:203], v151 offset:21504
	ds_read_b128 v[204:207], v151 offset:22528
	ds_read_b128 v[208:211], v151 offset:23552
	global_load_lds_dwordx4 v[144:145], off
	s_add_i32 m0, s60, 0x2000
	s_add_u32 s60, s10, 0x80000
	v_lshl_add_u64 v[212:213], s[10:11], 0, v[134:135]
	s_addc_u32 s61, s11, 0
	s_add_i32 s62, s62, s4
	global_load_lds_dwordx4 v[212:213], off
	s_mov_b32 m0, s62
	v_lshl_add_u64 v[216:217], s[52:53], 0, v[132:133]
	global_load_lds_dwordx4 v0, s[60:61]
	s_add_i32 m0, s62, 0x2000
	s_nop 0
	global_load_lds_dwordx4 v134, s[60:61]
	v_lshl_add_u64 v[214:215], s[52:53], 0, v[130:131]
	s_mov_b32 m0, s5
	s_nop 0
	global_load_lds_dwordx4 v[214:215], off
	s_mov_b32 m0, s6
	s_nop 0
	global_load_lds_dwordx4 v[216:217], off
	s_waitcnt vmcnt(8)
	s_waitcnt lgkmcnt(0)
	s_setprio 1
	s_barrier
; #define PG8_STAGE(bufoff, gbase, voff) do { _Pragma("unroll") for (int _i = 0; _i < 2; ++_i) \
;         __builtin_amdgcn_global_load_lds((const unsigned*)((const char*)(gbase) + (voff)[_i]), (PG8_LAS unsigned*)(lds + (bufoff) + ldsw + _i * 8192), 16, 0, 0); } while (0)
; #define PG8_LDA(dst, b, h) do { _Pragma("unroll") for (int m = 0; m < 4; ++m) _Pragma("unroll") for (int k = 0; k < 2; ++k) dst[m][k] = *(const PG8_LAS bf16x8*)(lds + PG8_SA(b, h) + aoff + m * 2048 + k * 1024); } while (0)
; #define PG8_LDB(dst, b, h) do { _Pragma("unroll") for (int n = 0; n < 2; ++n) _Pragma("unroll") for (int k = 0; k < 2; ++k) dst[n][k] = *(const PG8_LAS bf16x8*)(lds + PG8_SB(b, h) + boff + n * 2048 + k * 1024); } while (0)
; #define PG8_MMA(ai, bj, At, Bt) do { __builtin_amdgcn_s_setprio(1); _Pragma("unroll") for (int m = 0; m < 4; ++m) _Pragma("unroll") for (int n = 0; n < 2; ++n) _Pragma("unroll") for (int k = 0; k < 2; ++k) \
;         acc[ai][bj][m][n] = __builtin_amdgcn_mfma_f32_16x16x32_bf16(Bt[n][k], At[m][k], acc[ai][bj][m][n], 0, 0, 0); __builtin_amdgcn_s_setprio(0); } while (0)
; #define PG8_WAIT_V(n) asm volatile("s_waitcnt vmcnt(" #n ")" ::: "memory")
; #define PG8_WAIT_L(n) asm volatile("s_waitcnt lgkmcnt(" #n ")" ::: "memory")
; #define PG8_BAR __builtin_amdgcn_s_barrier()
; #define PG8_SCHED __builtin_amdgcn_sched_barrier(0)
; template <class Epi, class Sched, bool ALIGN_EPI = false, bool SP2 = false>
; __device__ __forceinline__ void gemm_phase(PG8_LAS unsigned char* lds, const Gemm g, const Sched& S, const Epi& E) {
;     ...
;             PG8_WAIT_V(8); PG8_WAIT_L(0); PG8_BAR; PG8_MMA(1, 0, At, B0); PG8_MMA(1, 1, At, B1); PG8_BAR; PG8_SCHED;
;             PG8_LDB(B0, 1, 0); PG8_LDB(B1, 1, 1); PG8_SCHED; PG8_LDA(At, 1, 0); PG8_STAGE(PG8_SA(0, 1), a2 + hstep, voffA);
;             PG8_WAIT_V(8); PG8_WAIT_L(0); PG8_BAR; PG8_MMA(0, 0, At, B0); PG8_MMA(0, 1, At, B1); PG8_BAR; PG8_SCHED;
	v_mfma_f32_16x16x32_bf16 v[62:65], v[140:143], v[180:183], v[62:65]
	v_mfma_f32_16x16x32_bf16 v[58:61], v[156:159], v[180:183], v[58:61]
	v_mfma_f32_16x16x32_bf16 v[46:49], v[140:143], v[188:191], v[46:49]
	v_mfma_f32_16x16x32_bf16 v[42:45], v[156:159], v[188:191], v[42:45]
	v_mfma_f32_16x16x32_bf16 v[30:33], v[140:143], v[196:199], v[30:33]
	v_mfma_f32_16x16x32_bf16 v[26:29], v[156:159], v[196:199], v[26:29]
	v_mfma_f32_16x16x32_bf16 v[14:17], v[140:143], v[204:207], v[14:17]
	v_mfma_f32_16x16x32_bf16 v[10:13], v[156:159], v[204:207], v[10:13]
	v_mfma_f32_16x16x32_bf16 v[62:65], v[152:155], v[184:187], v[62:65]
	v_mfma_f32_16x16x32_bf16 v[58:61], v[160:163], v[184:187], v[58:61]
	v_mfma_f32_16x16x32_bf16 v[46:49], v[152:155], v[192:195], v[46:49]
	v_mfma_f32_16x16x32_bf16 v[42:45], v[160:163], v[192:195], v[42:45]
	v_mfma_f32_16x16x32_bf16 v[30:33], v[152:155], v[200:203], v[30:33]
	v_mfma_f32_16x16x32_bf16 v[26:29], v[160:163], v[200:203], v[26:29]
	v_mfma_f32_16x16x32_bf16 v[14:17], v[152:155], v[208:211], v[14:17]
	v_mfma_f32_16x16x32_bf16 v[10:13], v[160:163], v[208:211], v[10:13]
	v_mfma_f32_16x16x32_bf16 v[54:57], v[164:167], v[180:183], v[54:57]
	v_mfma_f32_16x16x32_bf16 v[50:53], v[172:175], v[180:183], v[50:53]
	v_mfma_f32_16x16x32_bf16 v[38:41], v[164:167], v[188:191], v[38:41]
	v_mfma_f32_16x16x32_bf16 v[34:37], v[172:175], v[188:191], v[34:37]
	v_mfma_f32_16x16x32_bf16 v[22:25], v[164:167], v[196:199], v[22:25]
	v_mfma_f32_16x16x32_bf16 v[18:21], v[172:175], v[196:199], v[18:21]
	v_mfma_f32_16x16x32_bf16 v[6:9], v[164:167], v[204:207], v[6:9]
	v_mfma_f32_16x16x32_bf16 v[2:5], v[172:175], v[204:207], v[2:5]
	v_mfma_f32_16x16x32_bf16 v[54:57], v[168:171], v[184:187], v[54:57]
	v_mfma_f32_16x16x32_bf16 v[50:53], v[176:179], v[184:187], v[50:53]
	v_mfma_f32_16x16x32_bf16 v[38:41], v[168:171], v[192:195], v[38:41]
	v_mfma_f32_16x16x32_bf16 v[34:37], v[176:179], v[192:195], v[34:37]
	v_mfma_f32_16x16x32_bf16 v[22:25], v[168:171], v[200:203], v[22:25]
	v_mfma_f32_16x16x32_bf16 v[18:21], v[176:179], v[200:203], v[18:21]
	v_mfma_f32_16x16x32_bf16 v[6:9], v[168:171], v[208:211], v[6:9]
	v_mfma_f32_16x16x32_bf16 v[2:5], v[176:179], v[208:211], v[2:5]
	s_barrier
	s_setprio 0
	s_add_i32 s60, 0, 0x18000
	v_add_u32_e32 v146, s60, v149
	s_add_i32 s61, 0, 0x1c000
	ds_read_b128 v[140:143], v146
	ds_read_b128 v[152:155], v146 offset:1024
	ds_read_b128 v[156:159], v146 offset:2048
	ds_read_b128 v[160:163], v146 offset:3072
	v_add_u32_e32 v146, s61, v149
	ds_read_b128 v[164:167], v146
	ds_read_b128 v[168:171], v146 offset:1024
	ds_read_b128 v[172:175], v146 offset:2048
	ds_read_b128 v[176:179], v146 offset:3072
	s_add_u32 s52, s52, 0x80000
	s_addc_u32 s53, s53, 0
	s_mov_b32 m0, s7
	ds_read_b128 v[180:183], v151 offset:32768
	ds_read_b128 v[184:187], v151 offset:33792
	ds_read_b128 v[188:191], v151 offset:34816
	ds_read_b128 v[192:195], v151 offset:35840
	ds_read_b128 v[196:199], v151 offset:36864
	ds_read_b128 v[200:203], v151 offset:37888
	ds_read_b128 v[204:207], v151 offset:38912
	ds_read_b128 v[208:211], v151 offset:39936
	global_load_lds_dwordx4 v130, s[52:53]
	s_mov_b32 m0, s17
	s_nop 0
	global_load_lds_dwordx4 v132, s[52:53]
	s_waitcnt vmcnt(8)
	s_waitcnt lgkmcnt(0)
	s_setprio 1
	s_barrier
	v_mfma_f32_16x16x32_bf16 v[126:129], v[140:143], v[180:183], v[126:129]
	v_mfma_f32_16x16x32_bf16 v[122:125], v[156:159], v[180:183], v[122:125]
	v_mfma_f32_16x16x32_bf16 v[110:113], v[140:143], v[188:191], v[110:113]
	v_mfma_f32_16x16x32_bf16 v[106:109], v[156:159], v[188:191], v[106:109]
	v_mfma_f32_16x16x32_bf16 v[94:97], v[140:143], v[196:199], v[94:97]
	v_mfma_f32_16x16x32_bf16 v[90:93], v[156:159], v[196:199], v[90:93]
	v_mfma_f32_16x16x32_bf16 v[78:81], v[140:143], v[204:207], v[78:81]
	v_mfma_f32_16x16x32_bf16 v[74:77], v[156:159], v[204:207], v[74:77]
	v_mfma_f32_16x16x32_bf16 v[126:129], v[152:155], v[184:187], v[126:129]
	v_mfma_f32_16x16x32_bf16 v[122:125], v[160:163], v[184:187], v[122:125]
	v_mfma_f32_16x16x32_bf16 v[110:113], v[152:155], v[192:195], v[110:113]
	v_mfma_f32_16x16x32_bf16 v[106:109], v[160:163], v[192:195], v[106:109]
	v_mfma_f32_16x16x32_bf16 v[94:97], v[152:155], v[200:203], v[94:97]
	v_mfma_f32_16x16x32_bf16 v[90:93], v[160:163], v[200:203], v[90:93]
	v_mfma_f32_16x16x32_bf16 v[78:81], v[152:155], v[208:211], v[78:81]
	v_mfma_f32_16x16x32_bf16 v[74:77], v[160:163], v[208:211], v[74:77]
	v_mfma_f32_16x16x32_bf16 v[118:121], v[164:167], v[180:183], v[118:121]
	v_mfma_f32_16x16x32_bf16 v[114:117], v[172:175], v[180:183], v[114:117]
	v_mfma_f32_16x16x32_bf16 v[102:105], v[164:167], v[188:191], v[102:105]
	v_mfma_f32_16x16x32_bf16 v[98:101], v[172:175], v[188:191], v[98:101]
	v_mfma_f32_16x16x32_bf16 v[86:89], v[164:167], v[196:199], v[86:89]
	v_mfma_f32_16x16x32_bf16 v[82:85], v[172:175], v[196:199], v[82:85]
	v_mfma_f32_16x16x32_bf16 v[70:73], v[164:167], v[204:207], v[70:73]
	v_mfma_f32_16x16x32_bf16 v[66:69], v[172:175], v[204:207], v[66:69]
	v_mfma_f32_16x16x32_bf16 v[118:121], v[168:171], v[184:187], v[118:121]
	v_mfma_f32_16x16x32_bf16 v[114:117], v[176:179], v[184:187], v[114:117]
	v_mfma_f32_16x16x32_bf16 v[102:105], v[168:171], v[192:195], v[102:105]
	v_mfma_f32_16x16x32_bf16 v[98:101], v[176:179], v[192:195], v[98:101]
	v_mfma_f32_16x16x32_bf16 v[86:89], v[168:171], v[200:203], v[86:89]
	v_mfma_f32_16x16x32_bf16 v[82:85], v[176:179], v[200:203], v[82:85]
	v_mfma_f32_16x16x32_bf16 v[70:73], v[168:171], v[208:211], v[70:73]
	v_mfma_f32_16x16x32_bf16 v[66:69], v[176:179], v[208:211], v[66:69]
	s_barrier
; #define PG8_STAGE(bufoff, gbase, voff) do { _Pragma("unroll") for (int _i = 0; _i < 2; ++_i) \
;         __builtin_amdgcn_global_load_lds((const unsigned*)((const char*)(gbase) + (voff)[_i]), (PG8_LAS unsigned*)(lds + (bufoff) + ldsw + _i * 8192), 16, 0, 0); } while (0)
; #define PG8_LDA(dst, b, h) do { _Pragma("unroll") for (int m = 0; m < 4; ++m) _Pragma("unroll") for (int k = 0; k < 2; ++k) dst[m][k] = *(const PG8_LAS bf16x8*)(lds + PG8_SA(b, h) + aoff + m * 2048 + k * 1024); } while (0)
; #define PG8_MMA(ai, bj, At, Bt) do { __builtin_amdgcn_s_setprio(1); _Pragma("unroll") for (int m = 0; m < 4; ++m) _Pragma("unroll") for (int n = 0; n < 2; ++n) _Pragma("unroll") for (int k = 0; k < 2; ++k) \
;         acc[ai][bj][m][n] = __builtin_amdgcn_mfma_f32_16x16x32_bf16(Bt[n][k], At[m][k], acc[ai][bj][m][n], 0, 0, 0); __builtin_amdgcn_s_setprio(0); } while (0)
; #define PG8_WAIT_V(n) asm volatile("s_waitcnt vmcnt(" #n ")" ::: "memory")
; #define PG8_WAIT_L(n) asm volatile("s_waitcnt lgkmcnt(" #n ")" ::: "memory")
; #define PG8_BAR __builtin_amdgcn_s_barrier()
; #define PG8_SCHED __builtin_amdgcn_sched_barrier(0)
; template <class Epi, class Sched, bool ALIGN_EPI = false, bool SP2 = false>
; __device__ __forceinline__ void gemm_phase(PG8_LAS unsigned char* lds, const Gemm g, const Sched& S, const Epi& E) {
;     ...
;             PG8_WAIT_V(8); PG8_WAIT_L(0); PG8_BAR; PG8_MMA(0, 0, At, B0); PG8_MMA(0, 1, At, B1); PG8_BAR; PG8_SCHED;
;             PG8_LDA(At, 1, 1); PG8_STAGE(PG8_SB(1, 0), b3, voffB); PG8_STAGE(PG8_SB(1, 1), b3 + hstep, voffB); PG8_STAGE(PG8_SA(1, 0), a3, voffA);
;             PG8_WAIT_V(8); PG8_WAIT_L(0); PG8_BAR; PG8_MMA(1, 0, At, B0); PG8_MMA(1, 1, At, B1); PG8_BAR; PG8_SCHED;
	s_setprio 0
	s_add_i32 s52, s60, s4
	v_lshl_add_u64 v[144:145], v[144:145], 0, s[34:35]
	s_mov_b32 m0, s52
	ds_read_b128 v[180:183], v151 offset:49152
	ds_read_b128 v[184:187], v151 offset:50176
	ds_read_b128 v[188:191], v151 offset:51200
	ds_read_b128 v[192:195], v151 offset:52224
	ds_read_b128 v[196:199], v151 offset:53248
	ds_read_b128 v[200:203], v151 offset:54272
	ds_read_b128 v[204:207], v151 offset:55296
	ds_read_b128 v[208:211], v151 offset:56320
	global_load_lds_dwordx4 v[144:145], off
	s_add_i32 m0, s52, 0x2000
	s_add_u32 s10, s10, 0x80080
	v_lshl_add_u64 v[144:145], v[212:213], 0, s[34:35]
	s_addc_u32 s11, s11, 0
	s_add_i32 s52, s61, s4
	global_load_lds_dwordx4 v[144:145], off
	s_mov_b32 m0, s52
	s_nop 0
	global_load_lds_dwordx4 v0, s[10:11]
	s_add_i32 m0, s52, 0x2000
	s_nop 0
	global_load_lds_dwordx4 v134, s[10:11]
	v_lshl_add_u64 v[144:145], v[214:215], 0, s[34:35]
	s_mov_b32 m0, s30
	s_nop 0
	global_load_lds_dwordx4 v[144:145], off
	v_lshl_add_u64 v[144:145], v[216:217], 0, s[34:35]
	s_mov_b32 m0, s47
	s_nop 0
	global_load_lds_dwordx4 v[144:145], off
	s_waitcnt vmcnt(8)
	s_waitcnt lgkmcnt(0)
	s_setprio 1
	s_barrier
	v_mfma_f32_16x16x32_bf16 v[62:65], v[140:143], v[180:183], v[62:65]
	v_mfma_f32_16x16x32_bf16 v[58:61], v[156:159], v[180:183], v[58:61]
	v_mfma_f32_16x16x32_bf16 v[46:49], v[140:143], v[188:191], v[46:49]
	v_mfma_f32_16x16x32_bf16 v[42:45], v[156:159], v[188:191], v[42:45]
	v_mfma_f32_16x16x32_bf16 v[30:33], v[140:143], v[196:199], v[30:33]
	v_mfma_f32_16x16x32_bf16 v[26:29], v[156:159], v[196:199], v[26:29]
	v_mfma_f32_16x16x32_bf16 v[14:17], v[140:143], v[204:207], v[14:17]
	v_mfma_f32_16x16x32_bf16 v[10:13], v[156:159], v[204:207], v[10:13]
	v_mfma_f32_16x16x32_bf16 v[62:65], v[152:155], v[184:187], v[62:65]
	v_mfma_f32_16x16x32_bf16 v[58:61], v[160:163], v[184:187], v[58:61]
	v_mfma_f32_16x16x32_bf16 v[46:49], v[152:155], v[192:195], v[46:49]
	v_mfma_f32_16x16x32_bf16 v[42:45], v[160:163], v[192:195], v[42:45]
	v_mfma_f32_16x16x32_bf16 v[30:33], v[152:155], v[200:203], v[30:33]
	v_mfma_f32_16x16x32_bf16 v[26:29], v[160:163], v[200:203], v[26:29]
	v_mfma_f32_16x16x32_bf16 v[14:17], v[152:155], v[208:211], v[14:17]
	v_mfma_f32_16x16x32_bf16 v[10:13], v[160:163], v[208:211], v[10:13]
	v_mfma_f32_16x16x32_bf16 v[54:57], v[164:167], v[180:183], v[54:57]
	v_mfma_f32_16x16x32_bf16 v[50:53], v[172:175], v[180:183], v[50:53]
	v_mfma_f32_16x16x32_bf16 v[38:41], v[164:167], v[188:191], v[38:41]
	v_mfma_f32_16x16x32_bf16 v[34:37], v[172:175], v[188:191], v[34:37]
	v_mfma_f32_16x16x32_bf16 v[22:25], v[164:167], v[196:199], v[22:25]
	v_mfma_f32_16x16x32_bf16 v[18:21], v[172:175], v[196:199], v[18:21]
	v_mfma_f32_16x16x32_bf16 v[6:9], v[164:167], v[204:207], v[6:9]
	v_mfma_f32_16x16x32_bf16 v[2:5], v[172:175], v[204:207], v[2:5]
	v_mfma_f32_16x16x32_bf16 v[54:57], v[168:171], v[184:187], v[54:57]
	v_mfma_f32_16x16x32_bf16 v[50:53], v[176:179], v[184:187], v[50:53]
	v_mfma_f32_16x16x32_bf16 v[38:41], v[168:171], v[192:195], v[38:41]
	v_mfma_f32_16x16x32_bf16 v[34:37], v[176:179], v[192:195], v[34:37]
	v_mfma_f32_16x16x32_bf16 v[22:25], v[168:171], v[200:203], v[22:25]
	v_mfma_f32_16x16x32_bf16 v[18:21], v[176:179], v[200:203], v[18:21]
	v_mfma_f32_16x16x32_bf16 v[6:9], v[168:171], v[208:211], v[6:9]
	v_mfma_f32_16x16x32_bf16 v[2:5], v[176:179], v[208:211], v[2:5]
	s_barrier
	s_setprio 0
	s_add_i32 s59, s59, 2
	s_add_u32 s50, s50, 0x100
	s_addc_u32 s51, s51, 0
	s_add_u32 s57, s57, 0x100
	s_addc_u32 s58, s58, 0
	s_cmp_gt_u32 s59, 29
	s_cbranch_scc0 .LBB0_559
	s_and_b64 vcc, exec, s[14:15]
	s_cbranch_vccz .LBB0_562
	s_barrier

; #define PG8_STAGE(bufoff, gbase, voff) do { _Pragma("unroll") for (int _i = 0; _i < 2; ++_i) \
;         __builtin_amdgcn_global_load_lds((const unsigned*)((const char*)(gbase) + (voff)[_i]), (PG8_LAS unsigned*)(lds + (bufoff) + ldsw + _i * 8192), 16, 0, 0); } while (0)
; #define PG8_LDA(dst, b, h) do { _Pragma("unroll") for (int m = 0; m < 4; ++m) _Pragma("unroll") for (int k = 0; k < 2; ++k) dst[m][k] = *(const PG8_LAS bf16x8*)(lds + PG8_SA(b, h) + aoff + m * 2048 + k * 1024); } while (0)
; #define PG8_LDB(dst, b, h) do { _Pragma("unroll") for (int n = 0; n < 2; ++n) _Pragma("unroll") for (int k = 0; k < 2; ++k) dst[n][k] = *(const PG8_LAS bf16x8*)(lds + PG8_SB(b, h) + boff + n * 2048 + k * 1024); } while (0)
; #define PG8_MMA(ai, bj, At, Bt) do { __builtin_amdgcn_s_setprio(1); _Pragma("unroll") for (int m = 0; m < 4; ++m) _Pragma("unroll") for (int n = 0; n < 2; ++n) _Pragma("unroll") for (int k = 0; k < 2; ++k) \
;         acc[ai][bj][m][n] = __builtin_amdgcn_mfma_f32_16x16x32_bf16(Bt[n][k], At[m][k], acc[ai][bj][m][n], 0, 0, 0); __builtin_amdgcn_s_setprio(0); } while (0)
; #define PG8_WAIT_V(n) asm volatile("s_waitcnt vmcnt(" #n ")" ::: "memory")
; #define PG8_WAIT_L(n) asm volatile("s_waitcnt lgkmcnt(" #n ")" ::: "memory")
; #define PG8_BAR __builtin_amdgcn_s_barrier()
; #define PG8_SCHED __builtin_amdgcn_sched_barrier(0)
; template <class Epi, class Sched, bool ALIGN_EPI = false, bool SP2 = false>
; __device__ __forceinline__ void gemm_phase(PG8_LAS unsigned char* lds, const Gemm g, const Sched& S, const Epi& E) {
;     ...
;             PG8_LDB(B0, 0, 0); PG8_LDB(B1, 0, 1); PG8_SCHED; PG8_LDA(At, 0, 0); PG8_STAGE(PG8_SA(1, 1), a1 + hstep, voffA);
;             PG8_WAIT_V(8); PG8_WAIT_L(0); PG8_BAR; PG8_MMA(0, 0, At, B0); PG8_MMA(0, 1, At, B1); PG8_BAR; PG8_SCHED;
;             PG8_LDA(At, 0, 1); PG8_STAGE(PG8_SB(0, 0), b2, voffB); PG8_STAGE(PG8_SB(0, 1), b2 + hstep, voffB); PG8_STAGE(PG8_SA(0, 0), a2, voffA);
;             PG8_WAIT_V(8); PG8_WAIT_L(0); PG8_BAR; PG8_MMA(1, 0, At, B0); PG8_MMA(1, 1, At, B1); PG8_BAR; PG8_SCHED;
.LBB0_599:
	s_add_u32 s10, s36, 0xfff80080
	s_addc_u32 s11, s37, -1
	s_add_i32 s55, 0, 0x10000
	s_cmp_eq_u32 s54, 28
	s_cselect_b32 s41, s19, s11
	s_cselect_b32 s40, s50, s10
	v_add_u32_e32 v140, s55, v143
	s_cselect_b32 s11, s17, s53
	s_cselect_b32 s10, s51, s52
	s_add_i32 s58, 0, 0x14000
	ds_read_b128 v[146:149], v140
	ds_read_b128 v[150:153], v140 offset:1024
	ds_read_b128 v[154:157], v140 offset:2048
	ds_read_b128 v[158:161], v140 offset:3072
	v_add_u32_e32 v140, s58, v143
	ds_read_b128 v[162:165], v140
	ds_read_b128 v[166:169], v140 offset:1024
	ds_read_b128 v[170:173], v140 offset:2048
	ds_read_b128 v[174:177], v140 offset:3072
	s_add_i32 m0, s7, 0xc000
	ds_read_b128 v[178:181], v145
	ds_read_b128 v[182:185], v145 offset:1024
	ds_read_b128 v[186:189], v145 offset:2048
	ds_read_b128 v[190:193], v145 offset:3072
	ds_read_b128 v[194:197], v145 offset:4096
	ds_read_b128 v[198:201], v145 offset:5120
	ds_read_b128 v[202:205], v145 offset:6144
	ds_read_b128 v[206:209], v145 offset:7168
	global_load_lds_dwordx4 v136, s[36:37]
	s_add_i32 m0, s7, 0xe000
	s_nop 0
	global_load_lds_dwordx4 v138, s[36:37]
	s_waitcnt vmcnt(8)
	s_waitcnt lgkmcnt(0)
	s_setprio 1
	s_barrier
	v_mfma_f32_16x16x32_bf16 v[126:129], v[146:149], v[178:181], v[126:129]
	v_mfma_f32_16x16x32_bf16 v[122:125], v[154:157], v[178:181], v[122:125]
	v_mfma_f32_16x16x32_bf16 v[118:121], v[146:149], v[186:189], v[118:121]
	v_mfma_f32_16x16x32_bf16 v[110:113], v[154:157], v[186:189], v[110:113]
	v_mfma_f32_16x16x32_bf16 v[102:105], v[146:149], v[194:197], v[102:105]
	v_mfma_f32_16x16x32_bf16 v[94:97], v[154:157], v[194:197], v[94:97]
	v_mfma_f32_16x16x32_bf16 v[86:89], v[146:149], v[202:205], v[86:89]
	v_mfma_f32_16x16x32_bf16 v[78:81], v[154:157], v[202:205], v[78:81]
	v_mfma_f32_16x16x32_bf16 v[126:129], v[150:153], v[182:185], v[126:129]
	v_mfma_f32_16x16x32_bf16 v[122:125], v[158:161], v[182:185], v[122:125]
	v_mfma_f32_16x16x32_bf16 v[118:121], v[150:153], v[190:193], v[118:121]
	v_mfma_f32_16x16x32_bf16 v[110:113], v[158:161], v[190:193], v[110:113]
	v_mfma_f32_16x16x32_bf16 v[102:105], v[150:153], v[198:201], v[102:105]
	v_mfma_f32_16x16x32_bf16 v[94:97], v[158:161], v[198:201], v[94:97]
	v_mfma_f32_16x16x32_bf16 v[86:89], v[150:153], v[206:209], v[86:89]
	v_mfma_f32_16x16x32_bf16 v[78:81], v[158:161], v[206:209], v[78:81]
	v_mfma_f32_16x16x32_bf16 v[114:117], v[162:165], v[178:181], v[114:117]
	v_mfma_f32_16x16x32_bf16 v[106:109], v[170:173], v[178:181], v[106:109]
	v_mfma_f32_16x16x32_bf16 v[98:101], v[162:165], v[186:189], v[98:101]
	v_mfma_f32_16x16x32_bf16 v[90:93], v[170:173], v[186:189], v[90:93]
	v_mfma_f32_16x16x32_bf16 v[82:85], v[162:165], v[194:197], v[82:85]
	v_mfma_f32_16x16x32_bf16 v[74:77], v[170:173], v[194:197], v[74:77]
	v_mfma_f32_16x16x32_bf16 v[70:73], v[162:165], v[202:205], v[70:73]
	v_mfma_f32_16x16x32_bf16 v[66:69], v[170:173], v[202:205], v[66:69]
	v_mfma_f32_16x16x32_bf16 v[114:117], v[166:169], v[182:185], v[114:117]
	v_mfma_f32_16x16x32_bf16 v[106:109], v[174:177], v[182:185], v[106:109]
	v_mfma_f32_16x16x32_bf16 v[98:101], v[166:169], v[190:193], v[98:101]
	v_mfma_f32_16x16x32_bf16 v[90:93], v[174:177], v[190:193], v[90:93]
	v_mfma_f32_16x16x32_bf16 v[82:85], v[166:169], v[198:201], v[82:85]
	v_mfma_f32_16x16x32_bf16 v[74:77], v[174:177], v[198:201], v[74:77]
	v_mfma_f32_16x16x32_bf16 v[70:73], v[166:169], v[206:209], v[70:73]
	v_mfma_f32_16x16x32_bf16 v[66:69], v[174:177], v[206:209], v[66:69]
	s_barrier
	s_setprio 0
	s_add_i32 s55, s55, s4
	v_lshl_add_u64 v[140:141], s[10:11], 0, v[0:1]
	s_mov_b32 m0, s55
	ds_read_b128 v[178:181], v145 offset:16384
	ds_read_b128 v[182:185], v145 offset:17408
	ds_read_b128 v[186:189], v145 offset:18432
	ds_read_b128 v[190:193], v145 offset:19456
	ds_read_b128 v[194:197], v145 offset:20480
	ds_read_b128 v[198:201], v145 offset:21504
	ds_read_b128 v[202:205], v145 offset:22528
	ds_read_b128 v[206:209], v145 offset:23552
	global_load_lds_dwordx4 v[140:141], off
	s_add_i32 m0, s55, 0x2000
	s_add_u32 s56, s10, 0x80000
	v_lshl_add_u64 v[210:211], s[10:11], 0, v[134:135]
	s_addc_u32 s57, s11, 0
	s_add_i32 s55, s58, s4
	global_load_lds_dwordx4 v[210:211], off
	s_mov_b32 m0, s55
	v_lshl_add_u64 v[214:215], s[40:41], 0, v[132:133]
	global_load_lds_dwordx4 v0, s[56:57]
	s_add_i32 m0, s55, 0x2000
	s_nop 0
	global_load_lds_dwordx4 v134, s[56:57]
	v_lshl_add_u64 v[212:213], s[40:41], 0, v[130:131]
	s_mov_b32 m0, s7
	s_nop 0
	global_load_lds_dwordx4 v[212:213], off
	s_mov_b32 m0, s21
	s_nop 0
	global_load_lds_dwordx4 v[214:215], off
	s_waitcnt vmcnt(8)
	s_waitcnt lgkmcnt(0)
	s_setprio 1
	s_barrier
; #define PG8_STAGE(bufoff, gbase, voff) do { _Pragma("unroll") for (int _i = 0; _i < 2; ++_i) \
;         __builtin_amdgcn_global_load_lds((const unsigned*)((const char*)(gbase) + (voff)[_i]), (PG8_LAS unsigned*)(lds + (bufoff) + ldsw + _i * 8192), 16, 0, 0); } while (0)
; #define PG8_LDA(dst, b, h) do { _Pragma("unroll") for (int m = 0; m < 4; ++m) _Pragma("unroll") for (int k = 0; k < 2; ++k) dst[m][k] = *(const PG8_LAS bf16x8*)(lds + PG8_SA(b, h) + aoff + m * 2048 + k * 1024); } while (0)
; #define PG8_LDB(dst, b, h) do { _Pragma("unroll") for (int n = 0; n < 2; ++n) _Pragma("unroll") for (int k = 0; k < 2; ++k) dst[n][k] = *(const PG8_LAS bf16x8*)(lds + PG8_SB(b, h) + boff + n * 2048 + k * 1024); } while (0)
; #define PG8_MMA(ai, bj, At, Bt) do { __builtin_amdgcn_s_setprio(1); _Pragma("unroll") for (int m = 0; m < 4; ++m) _Pragma("unroll") for (int n = 0; n < 2; ++n) _Pragma("unroll") for (int k = 0; k < 2; ++k) \
;         acc[ai][bj][m][n] = __builtin_amdgcn_mfma_f32_16x16x32_bf16(Bt[n][k], At[m][k], acc[ai][bj][m][n], 0, 0, 0); __builtin_amdgcn_s_setprio(0); } while (0)
; #define PG8_WAIT_V(n) asm volatile("s_waitcnt vmcnt(" #n ")" ::: "memory")
; #define PG8_WAIT_L(n) asm volatile("s_waitcnt lgkmcnt(" #n ")" ::: "memory")
; #define PG8_BAR __builtin_amdgcn_s_barrier()
; #define PG8_SCHED __builtin_amdgcn_sched_barrier(0)
; template <class Epi, class Sched, bool ALIGN_EPI = false, bool SP2 = false>
; __device__ __forceinline__ void gemm_phase(PG8_LAS unsigned char* lds, const Gemm g, const Sched& S, const Epi& E) {
;     ...
;             PG8_WAIT_V(8); PG8_WAIT_L(0); PG8_BAR; PG8_MMA(1, 0, At, B0); PG8_MMA(1, 1, At, B1); PG8_BAR; PG8_SCHED;
;             PG8_LDB(B0, 1, 0); PG8_LDB(B1, 1, 1); PG8_SCHED; PG8_LDA(At, 1, 0); PG8_STAGE(PG8_SA(0, 1), a2 + hstep, voffA);
;             PG8_WAIT_V(8); PG8_WAIT_L(0); PG8_BAR; PG8_MMA(0, 0, At, B0); PG8_MMA(0, 1, At, B1); PG8_BAR; PG8_SCHED;
	v_mfma_f32_16x16x32_bf16 v[62:65], v[146:149], v[178:181], v[62:65]
	v_mfma_f32_16x16x32_bf16 v[58:61], v[154:157], v[178:181], v[58:61]
	v_mfma_f32_16x16x32_bf16 v[54:57], v[146:149], v[186:189], v[54:57]
	v_mfma_f32_16x16x32_bf16 v[46:49], v[154:157], v[186:189], v[46:49]
	v_mfma_f32_16x16x32_bf16 v[38:41], v[146:149], v[194:197], v[38:41]
	v_mfma_f32_16x16x32_bf16 v[30:33], v[154:157], v[194:197], v[30:33]
	v_mfma_f32_16x16x32_bf16 v[22:25], v[146:149], v[202:205], v[22:25]
	v_mfma_f32_16x16x32_bf16 v[14:17], v[154:157], v[202:205], v[14:17]
	v_mfma_f32_16x16x32_bf16 v[62:65], v[150:153], v[182:185], v[62:65]
	v_mfma_f32_16x16x32_bf16 v[58:61], v[158:161], v[182:185], v[58:61]
	v_mfma_f32_16x16x32_bf16 v[54:57], v[150:153], v[190:193], v[54:57]
	v_mfma_f32_16x16x32_bf16 v[46:49], v[158:161], v[190:193], v[46:49]
	v_mfma_f32_16x16x32_bf16 v[38:41], v[150:153], v[198:201], v[38:41]
	v_mfma_f32_16x16x32_bf16 v[30:33], v[158:161], v[198:201], v[30:33]
	v_mfma_f32_16x16x32_bf16 v[22:25], v[150:153], v[206:209], v[22:25]
	v_mfma_f32_16x16x32_bf16 v[14:17], v[158:161], v[206:209], v[14:17]
	v_mfma_f32_16x16x32_bf16 v[50:53], v[162:165], v[178:181], v[50:53]
	v_mfma_f32_16x16x32_bf16 v[42:45], v[170:173], v[178:181], v[42:45]
	v_mfma_f32_16x16x32_bf16 v[34:37], v[162:165], v[186:189], v[34:37]
	v_mfma_f32_16x16x32_bf16 v[26:29], v[170:173], v[186:189], v[26:29]
	v_mfma_f32_16x16x32_bf16 v[18:21], v[162:165], v[194:197], v[18:21]
	v_mfma_f32_16x16x32_bf16 v[10:13], v[170:173], v[194:197], v[10:13]
	v_mfma_f32_16x16x32_bf16 v[6:9], v[162:165], v[202:205], v[6:9]
	v_mfma_f32_16x16x32_bf16 v[2:5], v[170:173], v[202:205], v[2:5]
	v_mfma_f32_16x16x32_bf16 v[50:53], v[166:169], v[182:185], v[50:53]
	v_mfma_f32_16x16x32_bf16 v[42:45], v[174:177], v[182:185], v[42:45]
	v_mfma_f32_16x16x32_bf16 v[34:37], v[166:169], v[190:193], v[34:37]
	v_mfma_f32_16x16x32_bf16 v[26:29], v[174:177], v[190:193], v[26:29]
	v_mfma_f32_16x16x32_bf16 v[18:21], v[166:169], v[198:201], v[18:21]
	v_mfma_f32_16x16x32_bf16 v[10:13], v[174:177], v[198:201], v[10:13]
	v_mfma_f32_16x16x32_bf16 v[6:9], v[166:169], v[206:209], v[6:9]
	v_mfma_f32_16x16x32_bf16 v[2:5], v[174:177], v[206:209], v[2:5]
	s_barrier
	s_setprio 0
	s_add_i32 s55, 0, 0x18000
	s_add_i32 s56, 0, 0x1c000
	v_add_u32_e32 v158, s55, v143
	v_add_u32_e32 v174, s56, v143
	ds_read_b128 v[146:149], v158
	ds_read_b128 v[150:153], v158 offset:1024
	ds_read_b128 v[154:157], v158 offset:2048
	ds_read_b128 v[158:161], v158 offset:3072
	ds_read_b128 v[162:165], v174
	ds_read_b128 v[166:169], v174 offset:1024
	ds_read_b128 v[170:173], v174 offset:2048
	ds_read_b128 v[174:177], v174 offset:3072
	s_add_u32 s40, s40, 0x80000
	s_addc_u32 s41, s41, 0
	s_mov_b32 m0, s30
	ds_read_b128 v[178:181], v145 offset:32768
	ds_read_b128 v[182:185], v145 offset:33792
	ds_read_b128 v[186:189], v145 offset:34816
	ds_read_b128 v[190:193], v145 offset:35840
	ds_read_b128 v[194:197], v145 offset:36864
	ds_read_b128 v[198:201], v145 offset:37888
	ds_read_b128 v[202:205], v145 offset:38912
	ds_read_b128 v[206:209], v145 offset:39936
	global_load_lds_dwordx4 v130, s[40:41]
	s_mov_b32 m0, s42
	s_nop 0
	global_load_lds_dwordx4 v132, s[40:41]
	s_waitcnt vmcnt(8)
	s_waitcnt lgkmcnt(0)
	s_setprio 1
	s_barrier
	v_mfma_f32_16x16x32_bf16 v[126:129], v[146:149], v[178:181], v[126:129]
	v_mfma_f32_16x16x32_bf16 v[122:125], v[154:157], v[178:181], v[122:125]
	v_mfma_f32_16x16x32_bf16 v[118:121], v[146:149], v[186:189], v[118:121]
	v_mfma_f32_16x16x32_bf16 v[110:113], v[154:157], v[186:189], v[110:113]
	v_mfma_f32_16x16x32_bf16 v[102:105], v[146:149], v[194:197], v[102:105]
	v_mfma_f32_16x16x32_bf16 v[94:97], v[154:157], v[194:197], v[94:97]
	v_mfma_f32_16x16x32_bf16 v[86:89], v[146:149], v[202:205], v[86:89]
	v_mfma_f32_16x16x32_bf16 v[78:81], v[154:157], v[202:205], v[78:81]
	v_mfma_f32_16x16x32_bf16 v[126:129], v[150:153], v[182:185], v[126:129]
	v_mfma_f32_16x16x32_bf16 v[122:125], v[158:161], v[182:185], v[122:125]
	v_mfma_f32_16x16x32_bf16 v[118:121], v[150:153], v[190:193], v[118:121]
	v_mfma_f32_16x16x32_bf16 v[110:113], v[158:161], v[190:193], v[110:113]
	v_mfma_f32_16x16x32_bf16 v[102:105], v[150:153], v[198:201], v[102:105]
	v_mfma_f32_16x16x32_bf16 v[94:97], v[158:161], v[198:201], v[94:97]
	v_mfma_f32_16x16x32_bf16 v[86:89], v[150:153], v[206:209], v[86:89]
	v_mfma_f32_16x16x32_bf16 v[78:81], v[158:161], v[206:209], v[78:81]
	v_mfma_f32_16x16x32_bf16 v[114:117], v[162:165], v[178:181], v[114:117]
	v_mfma_f32_16x16x32_bf16 v[106:109], v[170:173], v[178:181], v[106:109]
	v_mfma_f32_16x16x32_bf16 v[98:101], v[162:165], v[186:189], v[98:101]
	v_mfma_f32_16x16x32_bf16 v[90:93], v[170:173], v[186:189], v[90:93]
	v_mfma_f32_16x16x32_bf16 v[82:85], v[162:165], v[194:197], v[82:85]
	v_mfma_f32_16x16x32_bf16 v[74:77], v[170:173], v[194:197], v[74:77]
	v_mfma_f32_16x16x32_bf16 v[70:73], v[162:165], v[202:205], v[70:73]
	v_mfma_f32_16x16x32_bf16 v[66:69], v[170:173], v[202:205], v[66:69]
	v_mfma_f32_16x16x32_bf16 v[114:117], v[166:169], v[182:185], v[114:117]
	v_mfma_f32_16x16x32_bf16 v[106:109], v[174:177], v[182:185], v[106:109]
	v_mfma_f32_16x16x32_bf16 v[98:101], v[166:169], v[190:193], v[98:101]
	v_mfma_f32_16x16x32_bf16 v[90:93], v[174:177], v[190:193], v[90:93]
	v_mfma_f32_16x16x32_bf16 v[82:85], v[166:169], v[198:201], v[82:85]
	v_mfma_f32_16x16x32_bf16 v[74:77], v[174:177], v[198:201], v[74:77]
	v_mfma_f32_16x16x32_bf16 v[70:73], v[166:169], v[206:209], v[70:73]
	v_mfma_f32_16x16x32_bf16 v[66:69], v[174:177], v[206:209], v[66:69]
	s_barrier
; #define PG8_STAGE(bufoff, gbase, voff) do { _Pragma("unroll") for (int _i = 0; _i < 2; ++_i) \
;         __builtin_amdgcn_global_load_lds((const unsigned*)((const char*)(gbase) + (voff)[_i]), (PG8_LAS unsigned*)(lds + (bufoff) + ldsw + _i * 8192), 16, 0, 0); } while (0)
; #define PG8_LDA(dst, b, h) do { _Pragma("unroll") for (int m = 0; m < 4; ++m) _Pragma("unroll") for (int k = 0; k < 2; ++k) dst[m][k] = *(const PG8_LAS bf16x8*)(lds + PG8_SA(b, h) + aoff + m * 2048 + k * 1024); } while (0)
; #define PG8_MMA(ai, bj, At, Bt) do { __builtin_amdgcn_s_setprio(1); _Pragma("unroll") for (int m = 0; m < 4; ++m) _Pragma("unroll") for (int n = 0; n < 2; ++n) _Pragma("unroll") for (int k = 0; k < 2; ++k) \
;         acc[ai][bj][m][n] = __builtin_amdgcn_mfma_f32_16x16x32_bf16(Bt[n][k], At[m][k], acc[ai][bj][m][n], 0, 0, 0); __builtin_amdgcn_s_setprio(0); } while (0)
; #define PG8_WAIT_V(n) asm volatile("s_waitcnt vmcnt(" #n ")" ::: "memory")
; #define PG8_WAIT_L(n) asm volatile("s_waitcnt lgkmcnt(" #n ")" ::: "memory")
; #define PG8_BAR __builtin_amdgcn_s_barrier()
; #define PG8_SCHED __builtin_amdgcn_sched_barrier(0)
; template <class Epi, class Sched, bool ALIGN_EPI = false, bool SP2 = false>
; __device__ __forceinline__ void gemm_phase(PG8_LAS unsigned char* lds, const Gemm g, const Sched& S, const Epi& E) {
;     ...
;             PG8_WAIT_V(8); PG8_WAIT_L(0); PG8_BAR; PG8_MMA(0, 0, At, B0); PG8_MMA(0, 1, At, B1); PG8_BAR; PG8_SCHED;
;             PG8_LDA(At, 1, 1); PG8_STAGE(PG8_SB(1, 0), b3, voffB); PG8_STAGE(PG8_SB(1, 1), b3 + hstep, voffB); PG8_STAGE(PG8_SA(1, 0), a3, voffA);
;             PG8_WAIT_V(8); PG8_WAIT_L(0); PG8_BAR; PG8_MMA(1, 0, At, B0); PG8_MMA(1, 1, At, B1); PG8_BAR; PG8_SCHED;
	s_setprio 0
	s_add_i32 s40, s55, s4
	v_lshl_add_u64 v[140:141], v[140:141], 0, s[34:35]
	s_mov_b32 m0, s40
	ds_read_b128 v[178:181], v145 offset:49152
	ds_read_b128 v[182:185], v145 offset:50176
	ds_read_b128 v[186:189], v145 offset:51200
	ds_read_b128 v[190:193], v145 offset:52224
	ds_read_b128 v[194:197], v145 offset:53248
	ds_read_b128 v[198:201], v145 offset:54272
	ds_read_b128 v[202:205], v145 offset:55296
	ds_read_b128 v[206:209], v145 offset:56320
	global_load_lds_dwordx4 v[140:141], off
	s_add_i32 m0, s40, 0x2000
	s_add_u32 s10, s10, 0x80080
	v_lshl_add_u64 v[140:141], v[210:211], 0, s[34:35]
	s_addc_u32 s11, s11, 0
	s_add_i32 s40, s56, s4
	global_load_lds_dwordx4 v[140:141], off
	s_mov_b32 m0, s40
	s_nop 0
	global_load_lds_dwordx4 v0, s[10:11]
	s_add_i32 m0, s40, 0x2000
	s_nop 0
	global_load_lds_dwordx4 v134, s[10:11]
	v_lshl_add_u64 v[140:141], v[212:213], 0, s[34:35]
	s_mov_b32 m0, s43
	s_nop 0
	global_load_lds_dwordx4 v[140:141], off
	v_lshl_add_u64 v[140:141], v[214:215], 0, s[34:35]
	s_mov_b32 m0, s44
	s_nop 0
	global_load_lds_dwordx4 v[140:141], off
	s_waitcnt vmcnt(8)
	s_waitcnt lgkmcnt(0)
	s_setprio 1
	s_barrier
	v_mfma_f32_16x16x32_bf16 v[62:65], v[146:149], v[178:181], v[62:65]
	v_mfma_f32_16x16x32_bf16 v[58:61], v[154:157], v[178:181], v[58:61]
	v_mfma_f32_16x16x32_bf16 v[54:57], v[146:149], v[186:189], v[54:57]
	v_mfma_f32_16x16x32_bf16 v[46:49], v[154:157], v[186:189], v[46:49]
	v_mfma_f32_16x16x32_bf16 v[38:41], v[146:149], v[194:197], v[38:41]
	v_mfma_f32_16x16x32_bf16 v[30:33], v[154:157], v[194:197], v[30:33]
	v_mfma_f32_16x16x32_bf16 v[22:25], v[146:149], v[202:205], v[22:25]
	v_mfma_f32_16x16x32_bf16 v[14:17], v[154:157], v[202:205], v[14:17]
	v_mfma_f32_16x16x32_bf16 v[62:65], v[150:153], v[182:185], v[62:65]
	v_mfma_f32_16x16x32_bf16 v[58:61], v[158:161], v[182:185], v[58:61]
	v_mfma_f32_16x16x32_bf16 v[54:57], v[150:153], v[190:193], v[54:57]
	v_mfma_f32_16x16x32_bf16 v[46:49], v[158:161], v[190:193], v[46:49]
	v_mfma_f32_16x16x32_bf16 v[38:41], v[150:153], v[198:201], v[38:41]
	v_mfma_f32_16x16x32_bf16 v[30:33], v[158:161], v[198:201], v[30:33]
	v_mfma_f32_16x16x32_bf16 v[22:25], v[150:153], v[206:209], v[22:25]
	v_mfma_f32_16x16x32_bf16 v[14:17], v[158:161], v[206:209], v[14:17]
	v_mfma_f32_16x16x32_bf16 v[50:53], v[162:165], v[178:181], v[50:53]
	v_mfma_f32_16x16x32_bf16 v[42:45], v[170:173], v[178:181], v[42:45]
	v_mfma_f32_16x16x32_bf16 v[34:37], v[162:165], v[186:189], v[34:37]
	v_mfma_f32_16x16x32_bf16 v[26:29], v[170:173], v[186:189], v[26:29]
	v_mfma_f32_16x16x32_bf16 v[18:21], v[162:165], v[194:197], v[18:21]
	v_mfma_f32_16x16x32_bf16 v[10:13], v[170:173], v[194:197], v[10:13]
	v_mfma_f32_16x16x32_bf16 v[6:9], v[162:165], v[202:205], v[6:9]
	v_mfma_f32_16x16x32_bf16 v[2:5], v[170:173], v[202:205], v[2:5]
	v_mfma_f32_16x16x32_bf16 v[50:53], v[166:169], v[182:185], v[50:53]
	v_mfma_f32_16x16x32_bf16 v[42:45], v[174:177], v[182:185], v[42:45]
	v_mfma_f32_16x16x32_bf16 v[34:37], v[166:169], v[190:193], v[34:37]
	v_mfma_f32_16x16x32_bf16 v[26:29], v[174:177], v[190:193], v[26:29]
	v_mfma_f32_16x16x32_bf16 v[18:21], v[166:169], v[198:201], v[18:21]
	v_mfma_f32_16x16x32_bf16 v[10:13], v[174:177], v[198:201], v[10:13]
	v_mfma_f32_16x16x32_bf16 v[6:9], v[166:169], v[206:209], v[6:9]
	v_mfma_f32_16x16x32_bf16 v[2:5], v[174:177], v[206:209], v[2:5]
	s_barrier
	s_setprio 0
	s_add_i32 s54, s54, 2
	s_add_u32 s36, s36, 0x100
	s_addc_u32 s37, s37, 0
	s_add_u32 s52, s52, 0x100
	s_addc_u32 s53, s53, 0
	s_cmp_gt_u32 s54, 29
	s_cbranch_scc0 .LBB0_599
	s_and_b64 vcc, exec, s[12:13]
	s_cbranch_vccz .LBB0_602
	s_barrier
